# bf16-row GEMM: previous tile's epilogue deferred into the next tile's first K-iteration load segments (peeled iteration, C=0 first MFMAs, no accumulator zeroing); coalesced stores
# speedup vs baseline: 1.0156x; 1.0070x over previous
.LBB0_387:
	s_andn2_b64 vcc, exec, s[12:13]
	s_cbranch_vccnz .LBB0_481
	v_writelane_b32 v157, s0, 0
	v_writelane_b32 v157, s2, 1
	v_writelane_b32 v157, s3, 2
	v_writelane_b32 v157, s32, 3
	v_writelane_b32 v157, s36, 4
	v_writelane_b32 v157, s37, 5
	v_writelane_b32 v157, s46, 6
	v_writelane_b32 v157, s53, 7
	v_writelane_b32 v157, s56, 8
	v_writelane_b32 v157, s82, 9
	v_writelane_b32 v157, s90, 10
	v_writelane_b32 v157, s91, 11
	v_writelane_b32 v157, s97, 12
	s_mov_b32 s37, 0
	v_ashrrev_i32_e32 v1, 31, v225
	v_lshrrev_b32_e32 v1, 26, v1
	v_add_u32_e32 v1, v225, v1
	v_ashrrev_i32_e32 v9, 6, v1
	v_bfe_i32 v1, v225, 27, 1
	v_lshlrev_b32_e32 v0, 4, v225
	v_lshrrev_b32_e32 v1, 22, v1
	v_add_u32_e32 v1, v0, v1
	v_and_b32_e32 v1, 0xfffffc00, v1
	v_sub_u32_e32 v1, v0, v1
	v_lshrrev_b32_e32 v2, 4, v1
	v_bitop3_b32 v1, v2, v1, 32 bitop3:0x6c
	v_ashrrev_i32_e32 v3, 31, v1
	v_lshrrev_b32_e32 v3, 26, v3
	v_add_u32_e32 v3, v1, v3
	v_lshlrev_b32_e32 v2, 3, v9
	v_ashrrev_i32_e32 v10, 6, v3
	v_and_b32_e32 v3, 0xc0, v3
	v_and_b32_e32 v2, -16, v2
	v_sub_u32_e32 v1, v1, v3
	v_add_u32_e32 v2, v10, v2
	v_ashrrev_i16_sdwa v1, v219, sext(v1) dst_sel:DWORD dst_unused:UNUSED_PAD src0_sel:DWORD src1_sel:BYTE_0
	v_lshlrev_b32_e32 v4, 5, v9
	v_bfe_i32 v11, v1, 0, 16
	v_lshlrev_b32_e32 v1, 1, v2
	v_lshrrev_b32_e32 v3, 2, v2
	v_and_b32_e32 v5, 3, v10
	s_mov_b32 s1, 0x1fffe0
	v_and_b32_e32 v4, 32, v4
	v_and_b32_e32 v1, 24, v1
	v_and_b32_e32 v3, 4, v3
	v_and_or_b32 v5, v2, s1, v5
	v_or3_b32 v1, v5, v3, v1
	v_add_lshl_u32 v3, v4, v11, 1
	v_add_u32_e32 v0, 0x2000, v0
	v_lshl_add_u32 v132, v1, 11, v3
	v_ashrrev_i32_e32 v1, 31, v0
	v_lshrrev_b32_e32 v1, 22, v1
	v_add_u32_e32 v1, v0, v1
	v_ashrrev_i32_e32 v12, 10, v1
	v_mul_i32_i24_e32 v1, 0x400, v12
	v_sub_u32_e32 v0, v0, v1
	v_lshrrev_b32_e32 v1, 4, v0
	v_bitop3_b32 v0, v1, v0, 32 bitop3:0x6c
	v_lshl_add_u32 v130, v2, 11, v3
	v_ashrrev_i32_e32 v2, 31, v0
	v_lshrrev_b32_e32 v2, 26, v2
	v_lshlrev_b32_e32 v1, 3, v12
	v_add_u32_e32 v2, v0, v2
	v_and_b32_e32 v1, -16, v1
	v_ashrrev_i32_e32 v13, 6, v2
	v_add_u32_e32 v1, v13, v1
	v_and_b32_e32 v2, 0xc0, v2
	v_and_b32_e32 v4, 3, v13
	s_ashr_i32 s29, s28, 6
	s_ashr_i32 s41, s40, 31
	s_ashr_i32 s11, s10, 31
	v_sub_u32_e32 v0, v0, v2
	v_and_or_b32 v4, v1, s1, v4
	s_ashr_i32 s1, s28, 8
	s_lshl_b32 s34, s29, 10
	s_lshl_b64 s[12:13], s[40:41], 19
	s_lshl_b64 s[14:15], s[10:11], 19
	v_ashrrev_i16_sdwa v0, v219, sext(v0) dst_sel:DWORD dst_unused:UNUSED_PAD src0_sel:DWORD src1_sel:BYTE_0
	s_add_u32 s14, s20, s14
	v_lshlrev_b32_e32 v3, 5, v12
	v_bfe_i32 v14, v0, 0, 16
	v_lshlrev_b32_e32 v0, 1, v1
	v_lshrrev_b32_e32 v2, 2, v1
	s_addc_u32 s15, s21, s15
	s_add_i32 s41, s34, 0
	v_and_b32_e32 v3, 32, v3
	v_and_b32_e32 v0, 24, v0
	v_and_b32_e32 v2, 4, v2
	s_add_i32 m0, s41, 0x10000
	v_or3_b32 v0, v4, v2, v0
	v_add_lshl_u32 v2, v3, v14, 1
	global_load_lds_dwordx4 v132, s[14:15]
	s_add_i32 m0, s41, 0x12000
	v_lshl_add_u32 v136, v0, 11, v2
	s_add_u32 s30, s14, 0x40000
	global_load_lds_dwordx4 v136, s[14:15]
	s_addc_u32 s31, s15, 0
	s_add_i32 m0, s41, 0x14000
	v_lshl_add_u32 v134, v1, 11, v2
	global_load_lds_dwordx4 v132, s[30:31]
	s_add_i32 m0, s41, 0x16000
	s_add_u32 s12, s62, s12
	s_addc_u32 s13, s63, s13
	s_add_i32 s60, s41, 0x2000
	global_load_lds_dwordx4 v136, s[30:31]
	s_mov_b32 m0, s41
	s_add_u32 s30, s12, 0x40000
	global_load_lds_dwordx4 v130, s[12:13]
	s_mov_b32 m0, s60
	s_addc_u32 s31, s13, 0
	s_add_i32 s61, s41, 0x4000
	global_load_lds_dwordx4 v134, s[12:13]
	s_mov_b32 m0, s61
	s_add_i32 s69, s41, 0x6000
	global_load_lds_dwordx4 v130, s[30:31]
	s_mov_b32 m0, s69
	v_mov_b32_e32 v133, v101
	global_load_lds_dwordx4 v134, s[30:31]
	v_mov_b32_e32 v137, v101
	v_mov_b32_e32 v131, v101
	v_mov_b32_e32 v135, v101
	s_cmp_eq_u32 s1, 1
	v_lshl_add_u64 v[6:7], s[14:15], 0, v[132:133]
	v_lshl_add_u64 v[4:5], s[14:15], 0, v[136:137]
	v_lshl_add_u64 v[0:1], s[12:13], 0, v[130:131]
	s_cselect_b64 s[42:43], -1, 0
	s_cmp_lg_u32 s1, 1
	v_lshl_add_u64 v[2:3], s[12:13], 0, v[134:135]
	s_cbranch_scc1 .LBB0_390
	s_barrier
.LBB0_390:
	s_xor_b64 s[50:51], s[6:7], -1
	v_readlane_b32 s6, v241, 0
	v_readlane_b32 s7, v241, 1
	s_xor_b64 s[58:59], s[6:7], -1
	s_ashr_i32 s27, s26, 31
	s_cmp_lg_u64 s[8:9], 0
	s_cselect_b64 s[64:65], -1, 0
	s_and_b32 s6, s29, 3
	s_add_i32 m0, s41, 0x18000
	v_lshl_add_u64 v[6:7], v[6:7], 0, s[86:87]
	s_lshl_b32 s84, s1, 6
	s_lshl_b32 s1, s1, 13
	s_lshl_b32 s85, s6, 5
	s_lshl_b32 s11, s6, 12
	s_waitcnt vmcnt(2)
	s_barrier
	global_load_lds_dwordx4 v[6:7], off
	v_lshl_add_u64 v[4:5], v[4:5], 0, s[86:87]
	s_add_i32 m0, s41, 0x1a000
	s_add_i32 s89, s41, 0x8000
	s_add_i32 s92, s41, 0xa000
	global_load_lds_dwordx4 v[4:5], off
	v_lshl_add_u64 v[0:1], v[0:1], 0, s[86:87]
	s_mov_b32 m0, s89
	s_add_u32 s6, s14, 0x40080
	global_load_lds_dwordx4 v[0:1], off
	v_lshl_add_u64 v[0:1], v[2:3], 0, s[86:87]
	s_mov_b32 m0, s92
	s_addc_u32 s7, s15, 0
	global_load_lds_dwordx4 v[0:1], off
	s_add_i32 m0, s41, 0x1c000
	v_lshl_add_u64 v[0:1], s[6:7], 0, v[132:133]
	global_load_lds_dwordx4 v[0:1], off
	v_lshl_add_u64 v[0:1], s[6:7], 0, v[136:137]
	s_add_i32 m0, s41, 0x1e000
	v_and_b32_e32 v139, 15, v224
	global_load_lds_dwordx4 v[0:1], off
	v_bfe_u32 v0, v224, 4, 2
	v_lshlrev_b32_e32 v1, 6, v139
	v_lshlrev_b32_e32 v2, 2, v224
	v_lshlrev_b32_e32 v138, 3, v0
	v_lshl_or_b32 v1, v0, 4, v1
	v_and_b32_e32 v2, 32, v2
	v_or_b32_e32 v0, v0, v139
	v_cmp_eq_u32_e64 s[6:7], 0, v0
	v_bitop3_b32 v0, v1, s1, v2 bitop3:0xde
	v_bitop3_b32 v154, s11, v1, v2 bitop3:0xf6
	v_cvt_f32_u32_e32 v1, s35
	v_mul_f32_e32 v2, 0x4f7ffffe, v8
	s_cmpk_lt_u32 s28, 0x100
	v_cvt_u32_f32_e32 v2, v2
	v_rcp_iflag_f32_e32 v1, v1
	s_cselect_b64 s[70:71], -1, 0
	s_lshr_b32 s1, s28, 4
	s_bfe_u32 s94, s29, 0x10001
	s_and_b32 s1, s1, 4
	v_mul_f32_e32 v1, 0x4f7ffffe, v1
	s_add_u32 s95, s8, s1
	v_cvt_u32_f32_e32 v1, v1
	s_addc_u32 s98, s9, 0
	s_sub_i32 s1, 0, s5
	v_readfirstlane_b32 s8, v2
	s_mul_i32 s1, s1, s8
	s_mul_hi_u32 s1, s8, s1
	s_add_i32 s99, s8, s1
	v_readfirstlane_b32 s8, v1
	v_lshlrev_b32_e32 v1, 14, v9
	v_and_b32_e32 v1, 0xffff8000, v1
	v_lshl_add_u32 v1, v10, 11, v1
	v_and_b32_e32 v2, 1, v9
	v_lshl_or_b32 v1, v2, 6, v1
	v_lshl_add_u32 v140, v11, 1, v1
	v_lshlrev_b32_e32 v1, 14, v12
	s_sub_i32 s1, 0, s35
	v_and_b32_e32 v1, 0xffff8000, v1
	s_waitcnt vmcnt(0)
	s_mul_i32 s1, s1, s8
	v_lshl_add_u32 v1, v13, 11, v1
	v_and_b32_e32 v2, 1, v12
	s_mul_hi_u32 s1, s8, s1
	v_lshl_or_b32 v1, v2, 6, v1
	s_mov_b32 s93, 0
	v_or_b32_e32 v155, s85, v138
	s_add_i32 s52, s8, s1
	v_mov_b32_e32 v141, v101
	v_lshl_add_u32 v142, v14, 1, v1
	v_mov_b32_e32 v143, v101
	v_add_u32_e32 v156, 0, v0
	s_barrier
	s_branch .LBB0_393

.LBB0_393:
	s_add_i32 s93, s93, 1
	s_mul_i32 s1, s93, s68
	s_mul_hi_u32 s8, s93, s83
	s_add_i32 s8, s8, s1
	s_mul_i32 s1, s93, s83
	s_add_u32 s28, s1, s88
	s_addc_u32 s29, s8, s96
	s_waitcnt lgkmcnt(0)
	v_mov_b64_e32 v[176:177], s[26:27]
	v_cmp_ge_i64_e32 vcc, s[28:29], v[176:177]
	v_cmp_lt_i64_e64 s[8:9], s[28:29], v[176:177]
	s_cbranch_vccnz .LBB0_395
	s_ashr_i32 s1, s28, 31
	s_lshr_b32 s1, s1, 29
	s_add_i32 s1, s28, s1
	s_ashr_i32 s11, s1, 3
	s_and_b32 s1, s1, -8
	s_sub_i32 s1, s28, s1
	s_lshr_b32 s28, s1, 31
	s_or_b32 s28, s39, s28
	s_mul_i32 s1, s28, s1
	s_add_i32 s1, s1, s11
	s_abs_i32 s28, s1
	s_mul_hi_u32 s29, s28, s99
	s_mul_i32 s30, s29, s5
	s_sub_i32 s28, s28, s30
	s_ashr_i32 s11, s1, 31
	s_add_i32 s30, s29, 1
	s_sub_i32 s31, s28, s5
	s_cmp_ge_u32 s28, s5
	s_cselect_b32 s29, s30, s29
	s_cselect_b32 s28, s31, s28
	s_add_i32 s30, s29, 1
	s_cmp_ge_u32 s28, s5
	s_cselect_b32 s28, s30, s29
	s_xor_b32 s28, s28, s11
	s_sub_i32 s11, s28, s11
	s_lshl_b32 s28, s11, 3
	s_sub_i32 s29, s48, s28
	s_min_i32 s29, s29, 8
	s_abs_i32 s30, s29
	v_cvt_f32_u32_e32 v176, s30
	s_sub_i32 s33, 0, s30
	s_mul_i32 s11, s11, s5
	s_sub_i32 s1, s1, s11
	v_rcp_iflag_f32_e32 v176, v176
	s_abs_i32 s31, s1
	s_xor_b32 s11, s1, s29
	s_ashr_i32 s11, s11, 31
	v_mul_f32_e32 v176, 0x4f7ffffe, v176
	v_cvt_u32_f32_e32 v176, v176
	s_nop 0
	v_readfirstlane_b32 s47, v176
	s_mul_i32 s33, s33, s47
	s_mul_hi_u32 s33, s47, s33
	s_add_i32 s47, s47, s33
	s_mul_hi_u32 s33, s31, s47
	s_mul_i32 s47, s33, s30
	s_sub_i32 s31, s31, s47
	s_add_i32 s47, s33, 1
	s_sub_i32 s54, s31, s30
	s_cmp_ge_u32 s31, s30
	s_cselect_b32 s33, s47, s33
	s_cselect_b32 s31, s54, s31
	s_add_i32 s47, s33, 1
	s_cmp_ge_u32 s31, s30
	s_cselect_b32 s30, s47, s33
	s_xor_b32 s30, s30, s11
	s_sub_i32 s72, s30, s11
	s_mul_i32 s11, s72, s29
	s_sub_i32 s1, s1, s11
	s_add_i32 s74, s1, s28
.LBB0_395:
	s_ashr_i32 s75, s74, 31
	s_lshl_b64 s[28:29], s[74:75], 19
	s_add_u32 s76, s62, s28
	s_addc_u32 s77, s63, s29
	s_and_b64 s[28:29], s[8:9], exec
	s_cselect_b32 s11, s77, s13
	s_cselect_b32 s30, s76, s12
	s_ashr_i32 s73, s72, 31
	s_lshl_b64 s[28:29], s[72:73], 19
	s_add_u32 s78, s20, s28
	s_addc_u32 s79, s21, s29
	s_and_b64 s[28:29], s[8:9], exec
	s_cselect_b32 s31, s79, s15
	s_cselect_b32 s47, s78, s14
	s_add_u32 s12, s12, 0x40080
	s_addc_u32 s13, s13, 0
	s_add_u32 s54, s14, 0x100
	s_addc_u32 s55, s15, 0
	s_mov_b32 s73, -2
	s_cmp_lg_u32 s37, 0
	s_cbranch_scc1 .Lmy_b16_pdefer
	s_add_u32 s1, s12, 0xfffc0080
	s_addc_u32 s14, s13, -1
	s_add_i32 s33, 0, 0x10000
	s_cmp_eq_u32 s73, 12
	s_cselect_b32 s29, s11, s14
	s_cselect_b32 s28, s30, s1
	v_add_u32_e32 v100, s33, v154
	s_cselect_b32 s15, s31, s55
	s_cselect_b32 s14, s47, s54
	s_add_i32 s1, 0, 0x14000
	ds_read_b128 v[144:147], v100
	ds_read_b128 v[148:151], v100 offset:1024
	ds_read_b128 v[158:161], v100 offset:2048
	ds_read_b128 v[162:165], v100 offset:3072
	v_add_u32_e32 v100, s1, v154
	ds_read_b128 v[166:169], v100
	ds_read_b128 v[170:173], v100 offset:1024
	ds_read_b128 v[174:177], v100 offset:2048
	ds_read_b128 v[178:181], v100 offset:3072
	v_lshl_add_u64 v[152:153], s[12:13], 0, v[140:141]
	s_add_i32 m0, s41, 0xc000
	ds_read_b128 v[182:185], v156
	ds_read_b128 v[186:189], v156 offset:1024
	ds_read_b128 v[190:193], v156 offset:2048
	ds_read_b128 v[194:197], v156 offset:3072
	ds_read_b128 v[198:201], v156 offset:4096
	ds_read_b128 v[202:205], v156 offset:5120
	ds_read_b128 v[208:211], v156 offset:6144
	ds_read_b128 v[226:229], v156 offset:7168
	global_load_lds_dwordx4 v[152:153], off
	v_lshl_add_u64 v[152:153], s[12:13], 0, v[142:143]
	s_add_i32 m0, s41, 0xe000
	s_nop 0
	global_load_lds_dwordx4 v[152:153], off
	s_waitcnt vmcnt(24)
	s_waitcnt lgkmcnt(0)
	s_barrier
	s_setprio 1
	s_waitcnt lgkmcnt(0)
	v_mfma_f32_16x16x32_bf16 v[126:129], v[144:147], v[182:185], 0
	v_mfma_f32_16x16x32_bf16 v[122:125], v[158:161], v[182:185], 0
	v_mfma_f32_16x16x32_bf16 v[110:113], v[144:147], v[190:193], 0
	v_mfma_f32_16x16x32_bf16 v[106:109], v[158:161], v[190:193], 0
	v_mfma_f32_16x16x32_bf16 v[92:95], v[144:147], v[198:201], 0
	v_mfma_f32_16x16x32_bf16 v[88:91], v[158:161], v[198:201], 0
	v_mfma_f32_16x16x32_bf16 v[76:79], v[144:147], v[208:211], 0
	v_mfma_f32_16x16x32_bf16 v[72:75], v[158:161], v[208:211], 0
	v_mfma_f32_16x16x32_bf16 v[126:129], v[148:151], v[186:189], v[126:129]
	v_mfma_f32_16x16x32_bf16 v[122:125], v[162:165], v[186:189], v[122:125]
	v_mfma_f32_16x16x32_bf16 v[110:113], v[148:151], v[194:197], v[110:113]
	v_mfma_f32_16x16x32_bf16 v[106:109], v[162:165], v[194:197], v[106:109]
	v_mfma_f32_16x16x32_bf16 v[92:95], v[148:151], v[202:205], v[92:95]
	v_mfma_f32_16x16x32_bf16 v[88:91], v[162:165], v[202:205], v[88:91]
	v_mfma_f32_16x16x32_bf16 v[76:79], v[148:151], v[226:229], v[76:79]
	v_mfma_f32_16x16x32_bf16 v[72:75], v[162:165], v[226:229], v[72:75]
	s_setprio 0
	s_setprio 1
	v_mfma_f32_16x16x32_bf16 v[118:121], v[166:169], v[182:185], 0
	v_mfma_f32_16x16x32_bf16 v[114:117], v[174:177], v[182:185], 0
	v_mfma_f32_16x16x32_bf16 v[102:105], v[166:169], v[190:193], 0
	v_mfma_f32_16x16x32_bf16 v[96:99], v[174:177], v[190:193], 0
	v_mfma_f32_16x16x32_bf16 v[84:87], v[166:169], v[198:201], 0
	v_mfma_f32_16x16x32_bf16 v[80:83], v[174:177], v[198:201], 0
	v_mfma_f32_16x16x32_bf16 v[68:71], v[166:169], v[208:211], 0
	v_mfma_f32_16x16x32_bf16 v[64:67], v[174:177], v[208:211], 0
	v_mfma_f32_16x16x32_bf16 v[118:121], v[170:173], v[186:189], v[118:121]
	v_mfma_f32_16x16x32_bf16 v[114:117], v[178:181], v[186:189], v[114:117]
	v_mfma_f32_16x16x32_bf16 v[102:105], v[170:173], v[194:197], v[102:105]
	v_mfma_f32_16x16x32_bf16 v[96:99], v[178:181], v[194:197], v[96:99]
	v_mfma_f32_16x16x32_bf16 v[84:87], v[170:173], v[202:205], v[84:87]
	v_mfma_f32_16x16x32_bf16 v[80:83], v[178:181], v[202:205], v[80:83]
	v_mfma_f32_16x16x32_bf16 v[68:71], v[170:173], v[226:229], v[68:71]
	v_mfma_f32_16x16x32_bf16 v[64:67], v[178:181], v[226:229], v[64:67]
	s_setprio 0
	s_barrier
	s_add_i32 s33, s33, s34
	v_lshl_add_u64 v[152:153], s[14:15], 0, v[132:133]
	s_mov_b32 m0, s33
	ds_read_b128 v[182:185], v156 offset:16384
	ds_read_b128 v[186:189], v156 offset:17408
	ds_read_b128 v[190:193], v156 offset:18432
	ds_read_b128 v[194:197], v156 offset:19456
	ds_read_b128 v[198:201], v156 offset:20480
	ds_read_b128 v[202:205], v156 offset:21504
	ds_read_b128 v[208:211], v156 offset:22528
	ds_read_b128 v[226:229], v156 offset:23552
	global_load_lds_dwordx4 v[152:153], off
	s_add_i32 m0, s33, 0x2000
	s_add_u32 s80, s14, 0x40000
	v_lshl_add_u64 v[212:213], s[14:15], 0, v[136:137]
	s_addc_u32 s81, s15, 0
	s_add_i32 s1, s1, s34
	global_load_lds_dwordx4 v[212:213], off
	v_lshl_add_u64 v[230:231], s[80:81], 0, v[132:133]
	s_mov_b32 m0, s1
	v_lshl_add_u64 v[232:233], s[28:29], 0, v[134:135]
	global_load_lds_dwordx4 v[230:231], off
	v_lshl_add_u64 v[230:231], s[80:81], 0, v[136:137]
	s_add_i32 m0, s1, 0x2000
	s_nop 0
	global_load_lds_dwordx4 v[230:231], off
	v_lshl_add_u64 v[230:231], s[28:29], 0, v[130:131]
	s_mov_b32 m0, s41
	s_nop 0
	global_load_lds_dwordx4 v[230:231], off
	s_mov_b32 m0, s60
	s_nop 0
	global_load_lds_dwordx4 v[232:233], off
	s_lshl_b32 s46, s40, 8
	s_add_i32 s46, s46, s84
	v_or_b32_e32 v100, s46, v139
	v_lshlrev_b32_e32 v100, 2, v100
	global_load_dword v236, v100, s[66:67]
	global_load_dword v237, v100, s[66:67] offset:64
	global_load_dword v238, v100, s[66:67] offset:128
	global_load_dword v239, v100, s[66:67] offset:192
	global_load_dword v240, v100, s[66:67] offset:512
	global_load_dword v244, v100, s[66:67] offset:576
	global_load_dword v245, v100, s[66:67] offset:640
	global_load_dword v246, v100, s[66:67] offset:704
	s_waitcnt vmcnt(32)
	s_waitcnt lgkmcnt(0)
	s_barrier
	s_setprio 1
	s_waitcnt lgkmcnt(0)
	v_mfma_f32_16x16x32_bf16 v[60:63], v[144:147], v[182:185], 0
	v_mfma_f32_16x16x32_bf16 v[56:59], v[158:161], v[182:185], 0
	v_mfma_f32_16x16x32_bf16 v[44:47], v[144:147], v[190:193], 0
	v_mfma_f32_16x16x32_bf16 v[40:43], v[158:161], v[190:193], 0
	v_mfma_f32_16x16x32_bf16 v[28:31], v[144:147], v[198:201], 0
	v_mfma_f32_16x16x32_bf16 v[24:27], v[158:161], v[198:201], 0
	v_mfma_f32_16x16x32_bf16 v[12:15], v[144:147], v[208:211], 0
	v_mfma_f32_16x16x32_bf16 v[8:11], v[158:161], v[208:211], 0
	v_mfma_f32_16x16x32_bf16 v[60:63], v[148:151], v[186:189], v[60:63]
	v_mfma_f32_16x16x32_bf16 v[56:59], v[162:165], v[186:189], v[56:59]
	v_mfma_f32_16x16x32_bf16 v[44:47], v[148:151], v[194:197], v[44:47]
	v_mfma_f32_16x16x32_bf16 v[40:43], v[162:165], v[194:197], v[40:43]
	v_mfma_f32_16x16x32_bf16 v[28:31], v[148:151], v[202:205], v[28:31]
	v_mfma_f32_16x16x32_bf16 v[24:27], v[162:165], v[202:205], v[24:27]
	v_mfma_f32_16x16x32_bf16 v[12:15], v[148:151], v[226:229], v[12:15]
	v_mfma_f32_16x16x32_bf16 v[8:11], v[162:165], v[226:229], v[8:11]
	s_setprio 0
	s_setprio 1
	v_mfma_f32_16x16x32_bf16 v[52:55], v[166:169], v[182:185], 0
	v_mfma_f32_16x16x32_bf16 v[48:51], v[174:177], v[182:185], 0
	v_mfma_f32_16x16x32_bf16 v[36:39], v[166:169], v[190:193], 0
	v_mfma_f32_16x16x32_bf16 v[32:35], v[174:177], v[190:193], 0
	v_mfma_f32_16x16x32_bf16 v[20:23], v[166:169], v[198:201], 0
	v_mfma_f32_16x16x32_bf16 v[16:19], v[174:177], v[198:201], 0
	v_mfma_f32_16x16x32_bf16 v[4:7], v[166:169], v[208:211], 0
	v_mfma_f32_16x16x32_bf16 v[0:3], v[174:177], v[208:211], 0
	v_mfma_f32_16x16x32_bf16 v[52:55], v[170:173], v[186:189], v[52:55]
	v_mfma_f32_16x16x32_bf16 v[48:51], v[178:181], v[186:189], v[48:51]
	v_mfma_f32_16x16x32_bf16 v[36:39], v[170:173], v[194:197], v[36:39]
	v_mfma_f32_16x16x32_bf16 v[32:35], v[178:181], v[194:197], v[32:35]
	v_mfma_f32_16x16x32_bf16 v[20:23], v[170:173], v[202:205], v[20:23]
	v_mfma_f32_16x16x32_bf16 v[16:19], v[178:181], v[202:205], v[16:19]
	v_mfma_f32_16x16x32_bf16 v[4:7], v[170:173], v[226:229], v[4:7]
	v_mfma_f32_16x16x32_bf16 v[0:3], v[178:181], v[226:229], v[0:3]
	s_setprio 0
	s_barrier
	s_add_i32 s1, 0, 0x18000
	v_add_u32_e32 v100, s1, v154
	s_add_i32 s33, 0, 0x1c000
	ds_read_b128 v[144:147], v100
	ds_read_b128 v[148:151], v100 offset:1024
	ds_read_b128 v[158:161], v100 offset:2048
	ds_read_b128 v[162:165], v100 offset:3072
	v_add_u32_e32 v100, s33, v154
	ds_read_b128 v[166:169], v100
	ds_read_b128 v[170:173], v100 offset:1024
	ds_read_b128 v[174:177], v100 offset:2048
	ds_read_b128 v[178:181], v100 offset:3072
	s_add_u32 s28, s28, 0x40000
	s_addc_u32 s29, s29, 0
	s_mov_b32 m0, s61
	v_lshl_add_u64 v[234:235], s[28:29], 0, v[130:131]
	ds_read_b128 v[182:185], v156 offset:32768
	ds_read_b128 v[186:189], v156 offset:33792
	ds_read_b128 v[190:193], v156 offset:34816
	ds_read_b128 v[194:197], v156 offset:35840
	ds_read_b128 v[198:201], v156 offset:36864
	ds_read_b128 v[202:205], v156 offset:37888
	ds_read_b128 v[208:211], v156 offset:38912
	ds_read_b128 v[226:229], v156 offset:39936
	global_load_lds_dwordx4 v[234:235], off
	v_lshl_add_u64 v[234:235], s[28:29], 0, v[134:135]
	s_mov_b32 m0, s69
	s_nop 0
	global_load_lds_dwordx4 v[234:235], off
	s_waitcnt vmcnt(16)
	s_waitcnt lgkmcnt(0)
	s_barrier
	s_setprio 1
	s_waitcnt lgkmcnt(0)
	v_mfma_f32_16x16x32_bf16 v[126:129], v[144:147], v[182:185], v[126:129]
	v_mfma_f32_16x16x32_bf16 v[122:125], v[158:161], v[182:185], v[122:125]
	v_mfma_f32_16x16x32_bf16 v[110:113], v[144:147], v[190:193], v[110:113]
	v_mfma_f32_16x16x32_bf16 v[106:109], v[158:161], v[190:193], v[106:109]
	v_mfma_f32_16x16x32_bf16 v[92:95], v[144:147], v[198:201], v[92:95]
	v_mfma_f32_16x16x32_bf16 v[88:91], v[158:161], v[198:201], v[88:91]
	v_mfma_f32_16x16x32_bf16 v[76:79], v[144:147], v[208:211], v[76:79]
	v_mfma_f32_16x16x32_bf16 v[72:75], v[158:161], v[208:211], v[72:75]
	v_mfma_f32_16x16x32_bf16 v[126:129], v[148:151], v[186:189], v[126:129]
	v_mfma_f32_16x16x32_bf16 v[122:125], v[162:165], v[186:189], v[122:125]
	v_mfma_f32_16x16x32_bf16 v[110:113], v[148:151], v[194:197], v[110:113]
	v_mfma_f32_16x16x32_bf16 v[106:109], v[162:165], v[194:197], v[106:109]
	v_mfma_f32_16x16x32_bf16 v[92:95], v[148:151], v[202:205], v[92:95]
	v_mfma_f32_16x16x32_bf16 v[88:91], v[162:165], v[202:205], v[88:91]
	v_mfma_f32_16x16x32_bf16 v[76:79], v[148:151], v[226:229], v[76:79]
	v_mfma_f32_16x16x32_bf16 v[72:75], v[162:165], v[226:229], v[72:75]
	s_setprio 0
	s_setprio 1
	v_mfma_f32_16x16x32_bf16 v[118:121], v[166:169], v[182:185], v[118:121]
	v_mfma_f32_16x16x32_bf16 v[114:117], v[174:177], v[182:185], v[114:117]
	v_mfma_f32_16x16x32_bf16 v[102:105], v[166:169], v[190:193], v[102:105]
	v_mfma_f32_16x16x32_bf16 v[96:99], v[174:177], v[190:193], v[96:99]
	v_mfma_f32_16x16x32_bf16 v[84:87], v[166:169], v[198:201], v[84:87]
	v_mfma_f32_16x16x32_bf16 v[80:83], v[174:177], v[198:201], v[80:83]
	v_mfma_f32_16x16x32_bf16 v[68:71], v[166:169], v[208:211], v[68:71]
	v_mfma_f32_16x16x32_bf16 v[64:67], v[174:177], v[208:211], v[64:67]
	v_mfma_f32_16x16x32_bf16 v[118:121], v[170:173], v[186:189], v[118:121]
	v_mfma_f32_16x16x32_bf16 v[114:117], v[178:181], v[186:189], v[114:117]
	v_mfma_f32_16x16x32_bf16 v[102:105], v[170:173], v[194:197], v[102:105]
	v_mfma_f32_16x16x32_bf16 v[96:99], v[178:181], v[194:197], v[96:99]
	v_mfma_f32_16x16x32_bf16 v[84:87], v[170:173], v[202:205], v[84:87]
	v_mfma_f32_16x16x32_bf16 v[80:83], v[178:181], v[202:205], v[80:83]
	v_mfma_f32_16x16x32_bf16 v[68:71], v[170:173], v[226:229], v[68:71]
	v_mfma_f32_16x16x32_bf16 v[64:67], v[178:181], v[226:229], v[64:67]
	s_setprio 0
	s_barrier
	s_add_i32 s1, s1, s34
	v_lshl_add_u64 v[152:153], v[152:153], 0, s[86:87]
	s_mov_b32 m0, s1
	ds_read_b128 v[182:185], v156 offset:49152
	ds_read_b128 v[186:189], v156 offset:50176
	ds_read_b128 v[190:193], v156 offset:51200
	ds_read_b128 v[194:197], v156 offset:52224
	ds_read_b128 v[198:201], v156 offset:53248
	ds_read_b128 v[202:205], v156 offset:54272
	ds_read_b128 v[208:211], v156 offset:55296
	ds_read_b128 v[226:229], v156 offset:56320
	global_load_lds_dwordx4 v[152:153], off
	s_add_i32 m0, s1, 0x2000
	s_add_u32 s14, s14, 0x40080
	v_lshl_add_u64 v[152:153], v[212:213], 0, s[86:87]
	s_addc_u32 s15, s15, 0
	s_add_i32 s1, s33, s34
	global_load_lds_dwordx4 v[152:153], off
	v_lshl_add_u64 v[152:153], s[14:15], 0, v[132:133]
	s_mov_b32 m0, s1
	s_nop 0
	global_load_lds_dwordx4 v[152:153], off
	v_lshl_add_u64 v[152:153], s[14:15], 0, v[136:137]
	s_add_i32 m0, s1, 0x2000
	s_nop 0
	global_load_lds_dwordx4 v[152:153], off
	v_lshl_add_u64 v[152:153], v[230:231], 0, s[86:87]
	s_mov_b32 m0, s89
	s_nop 0
	global_load_lds_dwordx4 v[152:153], off
	v_lshl_add_u64 v[152:153], v[232:233], 0, s[86:87]
	s_mov_b32 m0, s92
	s_nop 0
	global_load_lds_dwordx4 v[152:153], off
	s_waitcnt vmcnt(16)
	s_waitcnt lgkmcnt(0)
	s_barrier
	s_setprio 1
	s_waitcnt lgkmcnt(0)
	v_mfma_f32_16x16x32_bf16 v[60:63], v[144:147], v[182:185], v[60:63]
	v_mfma_f32_16x16x32_bf16 v[56:59], v[158:161], v[182:185], v[56:59]
	v_mfma_f32_16x16x32_bf16 v[44:47], v[144:147], v[190:193], v[44:47]
	v_mfma_f32_16x16x32_bf16 v[40:43], v[158:161], v[190:193], v[40:43]
	v_mfma_f32_16x16x32_bf16 v[28:31], v[144:147], v[198:201], v[28:31]
	v_mfma_f32_16x16x32_bf16 v[24:27], v[158:161], v[198:201], v[24:27]
	v_mfma_f32_16x16x32_bf16 v[12:15], v[144:147], v[208:211], v[12:15]
	v_mfma_f32_16x16x32_bf16 v[8:11], v[158:161], v[208:211], v[8:11]
	v_mfma_f32_16x16x32_bf16 v[60:63], v[148:151], v[186:189], v[60:63]
	v_mfma_f32_16x16x32_bf16 v[56:59], v[162:165], v[186:189], v[56:59]
	v_mfma_f32_16x16x32_bf16 v[44:47], v[148:151], v[194:197], v[44:47]
	v_mfma_f32_16x16x32_bf16 v[40:43], v[162:165], v[194:197], v[40:43]
	v_mfma_f32_16x16x32_bf16 v[28:31], v[148:151], v[202:205], v[28:31]
	v_mfma_f32_16x16x32_bf16 v[24:27], v[162:165], v[202:205], v[24:27]
	v_mfma_f32_16x16x32_bf16 v[12:15], v[148:151], v[226:229], v[12:15]
	v_mfma_f32_16x16x32_bf16 v[8:11], v[162:165], v[226:229], v[8:11]
	s_setprio 0
	s_setprio 1
	v_mfma_f32_16x16x32_bf16 v[52:55], v[166:169], v[182:185], v[52:55]
	v_mfma_f32_16x16x32_bf16 v[48:51], v[174:177], v[182:185], v[48:51]
	v_mfma_f32_16x16x32_bf16 v[36:39], v[166:169], v[190:193], v[36:39]
	v_mfma_f32_16x16x32_bf16 v[32:35], v[174:177], v[190:193], v[32:35]
	v_mfma_f32_16x16x32_bf16 v[20:23], v[166:169], v[198:201], v[20:23]
	v_mfma_f32_16x16x32_bf16 v[16:19], v[174:177], v[198:201], v[16:19]
	v_mfma_f32_16x16x32_bf16 v[4:7], v[166:169], v[208:211], v[4:7]
	v_mfma_f32_16x16x32_bf16 v[0:3], v[174:177], v[208:211], v[0:3]
	v_mfma_f32_16x16x32_bf16 v[52:55], v[170:173], v[186:189], v[52:55]
	v_mfma_f32_16x16x32_bf16 v[48:51], v[178:181], v[186:189], v[48:51]
	v_mfma_f32_16x16x32_bf16 v[36:39], v[170:173], v[194:197], v[36:39]
	v_mfma_f32_16x16x32_bf16 v[32:35], v[178:181], v[194:197], v[32:35]
	v_mfma_f32_16x16x32_bf16 v[20:23], v[170:173], v[202:205], v[20:23]
	v_mfma_f32_16x16x32_bf16 v[16:19], v[178:181], v[202:205], v[16:19]
	v_mfma_f32_16x16x32_bf16 v[4:7], v[170:173], v[226:229], v[4:7]
	v_mfma_f32_16x16x32_bf16 v[0:3], v[178:181], v[226:229], v[0:3]
	s_setprio 0
	s_barrier
	s_add_i32 s73, s73, 2
	s_add_u32 s12, s12, 0x100
	s_addc_u32 s13, s13, 0
	s_add_u32 s54, s54, 0x100
	s_addc_u32 s55, s55, 0
	s_branch .LBB0_396
.Lmy_b16_pdefer:
	s_add_u32 s1, s12, 0xfffc0080
	s_addc_u32 s14, s13, -1
	s_add_i32 s33, 0, 0x10000
	s_cmp_eq_u32 s73, 12
	s_cselect_b32 s29, s11, s14
	s_cselect_b32 s28, s30, s1
	v_add_u32_e32 v100, s33, v154
	s_cselect_b32 s15, s31, s55
	s_cselect_b32 s14, s47, s54
	s_add_i32 s1, 0, 0x14000
	ds_read_b128 v[144:147], v100
	ds_read_b128 v[148:151], v100 offset:1024
	ds_read_b128 v[158:161], v100 offset:2048
	ds_read_b128 v[162:165], v100 offset:3072
	v_add_u32_e32 v100, s1, v154
	ds_read_b128 v[166:169], v100
	ds_read_b128 v[170:173], v100 offset:1024
	ds_read_b128 v[174:177], v100 offset:2048
	ds_read_b128 v[178:181], v100 offset:3072
	v_lshl_add_u64 v[152:153], s[12:13], 0, v[140:141]
	s_add_i32 m0, s41, 0xc000
	ds_read_b128 v[182:185], v156
	ds_read_b128 v[186:189], v156 offset:1024
	ds_read_b128 v[190:193], v156 offset:2048
	ds_read_b128 v[194:197], v156 offset:3072
	ds_read_b128 v[198:201], v156 offset:4096
	ds_read_b128 v[202:205], v156 offset:5120
	ds_read_b128 v[208:211], v156 offset:6144
	ds_read_b128 v[226:229], v156 offset:7168
	global_load_lds_dwordx4 v[152:153], off
	v_lshl_add_u64 v[152:153], s[12:13], 0, v[142:143]
	s_add_i32 m0, s41, 0xe000
	s_nop 0
	global_load_lds_dwordx4 v[152:153], off
	v_and_b32_e32 v100, 3, v224
	v_lshlrev_b32_e32 v100, 6, v100
	v_and_or_b32 v100, v224, 60, v100
	v_mov_b32_e32 v152, v247
	v_add_u32_e32 v153, s32, v247
	v_fmamk_f32 v234, v236, 0x3a800000, v207
	v_rsq_f32_e32 v234, v234
	s_nop 0
	v_mul_f32_e32 v234, s36, v234
	v_pk_mul_f32 v[126:127], v[126:127], v[234:235] op_sel_hi:[1,0]
	v_pk_mul_f32 v[128:129], v[128:129], v[234:235] op_sel_hi:[1,0]
	v_pk_mul_f32 v[122:123], v[122:123], v[234:235] op_sel_hi:[1,0]
	v_pk_mul_f32 v[124:125], v[124:125], v[234:235] op_sel_hi:[1,0]
	v_cvt_pk_bf16_f32 v126, v126, v127
	v_cvt_pk_bf16_f32 v127, v128, v129
	v_cvt_pk_bf16_f32 v128, v122, v123
	v_cvt_pk_bf16_f32 v129, v124, v125
	ds_bpermute_b32 v122, v100, v126
	ds_bpermute_b32 v123, v100, v127
	ds_bpermute_b32 v124, v100, v128
	ds_bpermute_b32 v125, v100, v129
	v_pk_mul_f32 v[118:119], v[118:119], v[234:235] op_sel_hi:[1,0]
	v_pk_mul_f32 v[120:121], v[120:121], v[234:235] op_sel_hi:[1,0]
	v_pk_mul_f32 v[114:115], v[114:115], v[234:235] op_sel_hi:[1,0]
	v_pk_mul_f32 v[116:117], v[116:117], v[234:235] op_sel_hi:[1,0]
	v_cvt_pk_bf16_f32 v118, v118, v119
	v_cvt_pk_bf16_f32 v119, v120, v121
	v_cvt_pk_bf16_f32 v120, v114, v115
	v_cvt_pk_bf16_f32 v121, v116, v117
	ds_bpermute_b32 v114, v100, v118
	ds_bpermute_b32 v115, v100, v119
	ds_bpermute_b32 v116, v100, v120
	ds_bpermute_b32 v117, v100, v121
	s_waitcnt lgkmcnt(4)
	global_store_dwordx4 v152, v[122:125], s[2:3]
	v_add_u32_e32 v152, s0, v152
	v_fmamk_f32 v234, v237, 0x3a800000, v207
	v_rsq_f32_e32 v234, v234
	s_nop 0
	v_mul_f32_e32 v234, s36, v234
	v_pk_mul_f32 v[110:111], v[110:111], v[234:235] op_sel_hi:[1,0]
	v_pk_mul_f32 v[112:113], v[112:113], v[234:235] op_sel_hi:[1,0]
	v_pk_mul_f32 v[106:107], v[106:107], v[234:235] op_sel_hi:[1,0]
	v_pk_mul_f32 v[108:109], v[108:109], v[234:235] op_sel_hi:[1,0]
	v_cvt_pk_bf16_f32 v110, v110, v111
	v_cvt_pk_bf16_f32 v111, v112, v113
	v_cvt_pk_bf16_f32 v112, v106, v107
	v_cvt_pk_bf16_f32 v113, v108, v109
	ds_bpermute_b32 v106, v100, v110
	ds_bpermute_b32 v107, v100, v111
	ds_bpermute_b32 v108, v100, v112
	ds_bpermute_b32 v109, v100, v113
	s_waitcnt lgkmcnt(4)
	global_store_dwordx4 v153, v[114:117], s[2:3]
	v_add_u32_e32 v153, s0, v153
	v_pk_mul_f32 v[102:103], v[102:103], v[234:235] op_sel_hi:[1,0]
	v_pk_mul_f32 v[104:105], v[104:105], v[234:235] op_sel_hi:[1,0]
	v_pk_mul_f32 v[96:97], v[96:97], v[234:235] op_sel_hi:[1,0]
	v_pk_mul_f32 v[98:99], v[98:99], v[234:235] op_sel_hi:[1,0]
	v_cvt_pk_bf16_f32 v102, v102, v103
	v_cvt_pk_bf16_f32 v103, v104, v105
	v_cvt_pk_bf16_f32 v104, v96, v97
	v_cvt_pk_bf16_f32 v105, v98, v99
	ds_bpermute_b32 v96, v100, v102
	ds_bpermute_b32 v97, v100, v103
	ds_bpermute_b32 v98, v100, v104
	ds_bpermute_b32 v99, v100, v105
	s_waitcnt lgkmcnt(4)
	global_store_dwordx4 v152, v[106:109], s[2:3]
	v_add_u32_e32 v152, s0, v152
	v_fmamk_f32 v234, v238, 0x3a800000, v207
	v_rsq_f32_e32 v234, v234
	s_nop 0
	v_mul_f32_e32 v234, s36, v234
	v_pk_mul_f32 v[92:93], v[92:93], v[234:235] op_sel_hi:[1,0]
	v_pk_mul_f32 v[94:95], v[94:95], v[234:235] op_sel_hi:[1,0]
	v_pk_mul_f32 v[88:89], v[88:89], v[234:235] op_sel_hi:[1,0]
	v_pk_mul_f32 v[90:91], v[90:91], v[234:235] op_sel_hi:[1,0]
	v_cvt_pk_bf16_f32 v92, v92, v93
	v_cvt_pk_bf16_f32 v93, v94, v95
	v_cvt_pk_bf16_f32 v94, v88, v89
	v_cvt_pk_bf16_f32 v95, v90, v91
	ds_bpermute_b32 v88, v100, v92
	ds_bpermute_b32 v89, v100, v93
	ds_bpermute_b32 v90, v100, v94
	ds_bpermute_b32 v91, v100, v95
	s_waitcnt lgkmcnt(4)
	global_store_dwordx4 v153, v[96:99], s[2:3]
	v_add_u32_e32 v153, s0, v153
	v_pk_mul_f32 v[84:85], v[84:85], v[234:235] op_sel_hi:[1,0]
	v_pk_mul_f32 v[86:87], v[86:87], v[234:235] op_sel_hi:[1,0]
	v_pk_mul_f32 v[80:81], v[80:81], v[234:235] op_sel_hi:[1,0]
	v_pk_mul_f32 v[82:83], v[82:83], v[234:235] op_sel_hi:[1,0]
	v_cvt_pk_bf16_f32 v84, v84, v85
	v_cvt_pk_bf16_f32 v85, v86, v87
	v_cvt_pk_bf16_f32 v86, v80, v81
	v_cvt_pk_bf16_f32 v87, v82, v83
	ds_bpermute_b32 v80, v100, v84
	ds_bpermute_b32 v81, v100, v85
	ds_bpermute_b32 v82, v100, v86
	ds_bpermute_b32 v83, v100, v87
	s_waitcnt lgkmcnt(4)
	global_store_dwordx4 v152, v[88:91], s[2:3]
	v_add_u32_e32 v152, s0, v152
	v_fmamk_f32 v234, v239, 0x3a800000, v207
	v_rsq_f32_e32 v234, v234
	s_nop 0
	v_mul_f32_e32 v234, s36, v234
	v_pk_mul_f32 v[76:77], v[76:77], v[234:235] op_sel_hi:[1,0]
	v_pk_mul_f32 v[78:79], v[78:79], v[234:235] op_sel_hi:[1,0]
	v_pk_mul_f32 v[72:73], v[72:73], v[234:235] op_sel_hi:[1,0]
	v_pk_mul_f32 v[74:75], v[74:75], v[234:235] op_sel_hi:[1,0]
	v_cvt_pk_bf16_f32 v76, v76, v77
	v_cvt_pk_bf16_f32 v77, v78, v79
	v_cvt_pk_bf16_f32 v78, v72, v73
	v_cvt_pk_bf16_f32 v79, v74, v75
	ds_bpermute_b32 v72, v100, v76
	ds_bpermute_b32 v73, v100, v77
	ds_bpermute_b32 v74, v100, v78
	ds_bpermute_b32 v75, v100, v79
	s_waitcnt lgkmcnt(4)
	global_store_dwordx4 v153, v[80:83], s[2:3]
	v_add_u32_e32 v153, s0, v153
	v_pk_mul_f32 v[68:69], v[68:69], v[234:235] op_sel_hi:[1,0]
	v_pk_mul_f32 v[70:71], v[70:71], v[234:235] op_sel_hi:[1,0]
	v_pk_mul_f32 v[64:65], v[64:65], v[234:235] op_sel_hi:[1,0]
	v_pk_mul_f32 v[66:67], v[66:67], v[234:235] op_sel_hi:[1,0]
	v_cvt_pk_bf16_f32 v68, v68, v69
	v_cvt_pk_bf16_f32 v69, v70, v71
	v_cvt_pk_bf16_f32 v70, v64, v65
	v_cvt_pk_bf16_f32 v71, v66, v67
	ds_bpermute_b32 v64, v100, v68
	ds_bpermute_b32 v65, v100, v69
	ds_bpermute_b32 v66, v100, v70
	ds_bpermute_b32 v67, v100, v71
	s_waitcnt lgkmcnt(4)
	global_store_dwordx4 v152, v[72:75], s[2:3]
	v_add_u32_e32 v152, s0, v152
	s_waitcnt lgkmcnt(0)
	global_store_dwordx4 v153, v[64:67], s[2:3]
	s_waitcnt vmcnt(16)
	s_waitcnt lgkmcnt(0)
	s_barrier
	s_setprio 1
	s_waitcnt lgkmcnt(0)
	v_mfma_f32_16x16x32_bf16 v[126:129], v[144:147], v[182:185], 0
	v_mfma_f32_16x16x32_bf16 v[122:125], v[158:161], v[182:185], 0
	v_mfma_f32_16x16x32_bf16 v[110:113], v[144:147], v[190:193], 0
	v_mfma_f32_16x16x32_bf16 v[106:109], v[158:161], v[190:193], 0
	v_mfma_f32_16x16x32_bf16 v[92:95], v[144:147], v[198:201], 0
	v_mfma_f32_16x16x32_bf16 v[88:91], v[158:161], v[198:201], 0
	v_mfma_f32_16x16x32_bf16 v[76:79], v[144:147], v[208:211], 0
	v_mfma_f32_16x16x32_bf16 v[72:75], v[158:161], v[208:211], 0
	v_mfma_f32_16x16x32_bf16 v[126:129], v[148:151], v[186:189], v[126:129]
	v_mfma_f32_16x16x32_bf16 v[122:125], v[162:165], v[186:189], v[122:125]
	v_mfma_f32_16x16x32_bf16 v[110:113], v[148:151], v[194:197], v[110:113]
	v_mfma_f32_16x16x32_bf16 v[106:109], v[162:165], v[194:197], v[106:109]
	v_mfma_f32_16x16x32_bf16 v[92:95], v[148:151], v[202:205], v[92:95]
	v_mfma_f32_16x16x32_bf16 v[88:91], v[162:165], v[202:205], v[88:91]
	v_mfma_f32_16x16x32_bf16 v[76:79], v[148:151], v[226:229], v[76:79]
	v_mfma_f32_16x16x32_bf16 v[72:75], v[162:165], v[226:229], v[72:75]
	s_setprio 0
	s_setprio 1
	v_mfma_f32_16x16x32_bf16 v[118:121], v[166:169], v[182:185], 0
	v_mfma_f32_16x16x32_bf16 v[114:117], v[174:177], v[182:185], 0
	v_mfma_f32_16x16x32_bf16 v[102:105], v[166:169], v[190:193], 0
	v_mfma_f32_16x16x32_bf16 v[96:99], v[174:177], v[190:193], 0
	v_mfma_f32_16x16x32_bf16 v[84:87], v[166:169], v[198:201], 0
	v_mfma_f32_16x16x32_bf16 v[80:83], v[174:177], v[198:201], 0
	v_mfma_f32_16x16x32_bf16 v[68:71], v[166:169], v[208:211], 0
	v_mfma_f32_16x16x32_bf16 v[64:67], v[174:177], v[208:211], 0
	v_mfma_f32_16x16x32_bf16 v[118:121], v[170:173], v[186:189], v[118:121]
	v_mfma_f32_16x16x32_bf16 v[114:117], v[178:181], v[186:189], v[114:117]
	v_mfma_f32_16x16x32_bf16 v[102:105], v[170:173], v[194:197], v[102:105]
	v_mfma_f32_16x16x32_bf16 v[96:99], v[178:181], v[194:197], v[96:99]
	v_mfma_f32_16x16x32_bf16 v[84:87], v[170:173], v[202:205], v[84:87]
	v_mfma_f32_16x16x32_bf16 v[80:83], v[178:181], v[202:205], v[80:83]
	v_mfma_f32_16x16x32_bf16 v[68:71], v[170:173], v[226:229], v[68:71]
	v_mfma_f32_16x16x32_bf16 v[64:67], v[178:181], v[226:229], v[64:67]
	s_setprio 0
	s_barrier
	s_add_i32 s33, s33, s34
	v_lshl_add_u64 v[152:153], s[14:15], 0, v[132:133]
	s_mov_b32 m0, s33
	ds_read_b128 v[182:185], v156 offset:16384
	ds_read_b128 v[186:189], v156 offset:17408
	ds_read_b128 v[190:193], v156 offset:18432
	ds_read_b128 v[194:197], v156 offset:19456
	ds_read_b128 v[198:201], v156 offset:20480
	ds_read_b128 v[202:205], v156 offset:21504
	ds_read_b128 v[208:211], v156 offset:22528
	ds_read_b128 v[226:229], v156 offset:23552
	global_load_lds_dwordx4 v[152:153], off
	s_add_i32 m0, s33, 0x2000
	s_add_u32 s80, s14, 0x40000
	v_lshl_add_u64 v[212:213], s[14:15], 0, v[136:137]
	s_addc_u32 s81, s15, 0
	s_add_i32 s1, s1, s34
	global_load_lds_dwordx4 v[212:213], off
	v_lshl_add_u64 v[230:231], s[80:81], 0, v[132:133]
	s_mov_b32 m0, s1
	v_lshl_add_u64 v[232:233], s[28:29], 0, v[134:135]
	global_load_lds_dwordx4 v[230:231], off
	v_lshl_add_u64 v[230:231], s[80:81], 0, v[136:137]
	s_add_i32 m0, s1, 0x2000
	s_nop 0
	global_load_lds_dwordx4 v[230:231], off
	v_lshl_add_u64 v[230:231], s[28:29], 0, v[130:131]
	s_mov_b32 m0, s41
	s_nop 0
	global_load_lds_dwordx4 v[230:231], off
	s_mov_b32 m0, s60
	s_nop 0
	global_load_lds_dwordx4 v[232:233], off
	v_and_b32_e32 v100, 3, v224
	v_lshlrev_b32_e32 v100, 6, v100
	v_and_or_b32 v100, v224, 60, v100
	v_mov_b32_e32 v236, v247
	v_add_u32_e32 v237, s32, v247
	v_fmamk_f32 v234, v240, 0x3a800000, v207
	v_rsq_f32_e32 v234, v234
	s_nop 0
	v_mul_f32_e32 v234, s36, v234
	v_pk_mul_f32 v[60:61], v[60:61], v[234:235] op_sel_hi:[1,0]
	v_pk_mul_f32 v[62:63], v[62:63], v[234:235] op_sel_hi:[1,0]
	v_pk_mul_f32 v[56:57], v[56:57], v[234:235] op_sel_hi:[1,0]
	v_pk_mul_f32 v[58:59], v[58:59], v[234:235] op_sel_hi:[1,0]
	v_cvt_pk_bf16_f32 v60, v60, v61
	v_cvt_pk_bf16_f32 v61, v62, v63
	v_cvt_pk_bf16_f32 v62, v56, v57
	v_cvt_pk_bf16_f32 v63, v58, v59
	ds_bpermute_b32 v56, v100, v60
	ds_bpermute_b32 v57, v100, v61
	ds_bpermute_b32 v58, v100, v62
	ds_bpermute_b32 v59, v100, v63
	v_pk_mul_f32 v[52:53], v[52:53], v[234:235] op_sel_hi:[1,0]
	v_pk_mul_f32 v[54:55], v[54:55], v[234:235] op_sel_hi:[1,0]
	v_pk_mul_f32 v[48:49], v[48:49], v[234:235] op_sel_hi:[1,0]
	v_pk_mul_f32 v[50:51], v[50:51], v[234:235] op_sel_hi:[1,0]
	v_cvt_pk_bf16_f32 v52, v52, v53
	v_cvt_pk_bf16_f32 v53, v54, v55
	v_cvt_pk_bf16_f32 v54, v48, v49
	v_cvt_pk_bf16_f32 v55, v50, v51
	ds_bpermute_b32 v48, v100, v52
	ds_bpermute_b32 v49, v100, v53
	ds_bpermute_b32 v50, v100, v54
	ds_bpermute_b32 v51, v100, v55
	s_waitcnt lgkmcnt(4)
	global_store_dwordx4 v236, v[56:59], s[90:91]
	v_add_u32_e32 v236, s0, v236
	v_fmamk_f32 v234, v244, 0x3a800000, v207
	v_rsq_f32_e32 v234, v234
	s_nop 0
	v_mul_f32_e32 v234, s36, v234
	v_pk_mul_f32 v[44:45], v[44:45], v[234:235] op_sel_hi:[1,0]
	v_pk_mul_f32 v[46:47], v[46:47], v[234:235] op_sel_hi:[1,0]
	v_pk_mul_f32 v[40:41], v[40:41], v[234:235] op_sel_hi:[1,0]
	v_pk_mul_f32 v[42:43], v[42:43], v[234:235] op_sel_hi:[1,0]
	v_cvt_pk_bf16_f32 v44, v44, v45
	v_cvt_pk_bf16_f32 v45, v46, v47
	v_cvt_pk_bf16_f32 v46, v40, v41
	v_cvt_pk_bf16_f32 v47, v42, v43
	ds_bpermute_b32 v40, v100, v44
	ds_bpermute_b32 v41, v100, v45
	ds_bpermute_b32 v42, v100, v46
	ds_bpermute_b32 v43, v100, v47
	s_waitcnt lgkmcnt(4)
	global_store_dwordx4 v237, v[48:51], s[90:91]
	v_add_u32_e32 v237, s0, v237
	v_pk_mul_f32 v[36:37], v[36:37], v[234:235] op_sel_hi:[1,0]
	v_pk_mul_f32 v[38:39], v[38:39], v[234:235] op_sel_hi:[1,0]
	v_pk_mul_f32 v[32:33], v[32:33], v[234:235] op_sel_hi:[1,0]
	v_pk_mul_f32 v[34:35], v[34:35], v[234:235] op_sel_hi:[1,0]
	v_cvt_pk_bf16_f32 v36, v36, v37
	v_cvt_pk_bf16_f32 v37, v38, v39
	v_cvt_pk_bf16_f32 v38, v32, v33
	v_cvt_pk_bf16_f32 v39, v34, v35
	ds_bpermute_b32 v32, v100, v36
	ds_bpermute_b32 v33, v100, v37
	ds_bpermute_b32 v34, v100, v38
	ds_bpermute_b32 v35, v100, v39
	s_waitcnt lgkmcnt(4)
	global_store_dwordx4 v236, v[40:43], s[90:91]
	v_add_u32_e32 v236, s0, v236
	v_fmamk_f32 v234, v245, 0x3a800000, v207
	v_rsq_f32_e32 v234, v234
	s_nop 0
	v_mul_f32_e32 v234, s36, v234
	v_pk_mul_f32 v[28:29], v[28:29], v[234:235] op_sel_hi:[1,0]
	v_pk_mul_f32 v[30:31], v[30:31], v[234:235] op_sel_hi:[1,0]
	v_pk_mul_f32 v[24:25], v[24:25], v[234:235] op_sel_hi:[1,0]
	v_pk_mul_f32 v[26:27], v[26:27], v[234:235] op_sel_hi:[1,0]
	v_cvt_pk_bf16_f32 v28, v28, v29
	v_cvt_pk_bf16_f32 v29, v30, v31
	v_cvt_pk_bf16_f32 v30, v24, v25
	v_cvt_pk_bf16_f32 v31, v26, v27
	ds_bpermute_b32 v24, v100, v28
	ds_bpermute_b32 v25, v100, v29
	ds_bpermute_b32 v26, v100, v30
	ds_bpermute_b32 v27, v100, v31
	s_waitcnt lgkmcnt(4)
	global_store_dwordx4 v237, v[32:35], s[90:91]
	v_add_u32_e32 v237, s0, v237
	v_pk_mul_f32 v[20:21], v[20:21], v[234:235] op_sel_hi:[1,0]
	v_pk_mul_f32 v[22:23], v[22:23], v[234:235] op_sel_hi:[1,0]
	v_pk_mul_f32 v[16:17], v[16:17], v[234:235] op_sel_hi:[1,0]
	v_pk_mul_f32 v[18:19], v[18:19], v[234:235] op_sel_hi:[1,0]
	v_cvt_pk_bf16_f32 v20, v20, v21
	v_cvt_pk_bf16_f32 v21, v22, v23
	v_cvt_pk_bf16_f32 v22, v16, v17
	v_cvt_pk_bf16_f32 v23, v18, v19
	ds_bpermute_b32 v16, v100, v20
	ds_bpermute_b32 v17, v100, v21
	ds_bpermute_b32 v18, v100, v22
	ds_bpermute_b32 v19, v100, v23
	s_waitcnt lgkmcnt(4)
	global_store_dwordx4 v236, v[24:27], s[90:91]
	v_add_u32_e32 v236, s0, v236
	v_fmamk_f32 v234, v246, 0x3a800000, v207
	v_rsq_f32_e32 v234, v234
	s_nop 0
	v_mul_f32_e32 v234, s36, v234
	v_pk_mul_f32 v[12:13], v[12:13], v[234:235] op_sel_hi:[1,0]
	v_pk_mul_f32 v[14:15], v[14:15], v[234:235] op_sel_hi:[1,0]
	v_pk_mul_f32 v[8:9], v[8:9], v[234:235] op_sel_hi:[1,0]
	v_pk_mul_f32 v[10:11], v[10:11], v[234:235] op_sel_hi:[1,0]
	v_cvt_pk_bf16_f32 v12, v12, v13
	v_cvt_pk_bf16_f32 v13, v14, v15
	v_cvt_pk_bf16_f32 v14, v8, v9
	v_cvt_pk_bf16_f32 v15, v10, v11
	ds_bpermute_b32 v8, v100, v12
	ds_bpermute_b32 v9, v100, v13
	ds_bpermute_b32 v10, v100, v14
	ds_bpermute_b32 v11, v100, v15
	s_waitcnt lgkmcnt(4)
	global_store_dwordx4 v237, v[16:19], s[90:91]
	v_add_u32_e32 v237, s0, v237
	v_pk_mul_f32 v[4:5], v[4:5], v[234:235] op_sel_hi:[1,0]
	v_pk_mul_f32 v[6:7], v[6:7], v[234:235] op_sel_hi:[1,0]
	v_pk_mul_f32 v[0:1], v[0:1], v[234:235] op_sel_hi:[1,0]
	v_pk_mul_f32 v[2:3], v[2:3], v[234:235] op_sel_hi:[1,0]
	v_cvt_pk_bf16_f32 v4, v4, v5
	v_cvt_pk_bf16_f32 v5, v6, v7
	v_cvt_pk_bf16_f32 v6, v0, v1
	v_cvt_pk_bf16_f32 v7, v2, v3
	ds_bpermute_b32 v0, v100, v4
	ds_bpermute_b32 v1, v100, v5
	ds_bpermute_b32 v2, v100, v6
	ds_bpermute_b32 v3, v100, v7
	s_waitcnt lgkmcnt(4)
	global_store_dwordx4 v236, v[8:11], s[90:91]
	v_add_u32_e32 v236, s0, v236
	s_waitcnt lgkmcnt(0)
	global_store_dwordx4 v237, v[0:3], s[90:91]
	s_lshl_b32 s46, s40, 8
	s_add_i32 s46, s46, s84
	v_or_b32_e32 v100, s46, v139
	v_lshlrev_b32_e32 v100, 2, v100
	global_load_dword v236, v100, s[66:67]
	global_load_dword v237, v100, s[66:67] offset:64
	global_load_dword v238, v100, s[66:67] offset:128
	global_load_dword v239, v100, s[66:67] offset:192
	global_load_dword v240, v100, s[66:67] offset:512
	global_load_dword v244, v100, s[66:67] offset:576
	global_load_dword v245, v100, s[66:67] offset:640
	global_load_dword v246, v100, s[66:67] offset:704
	s_waitcnt vmcnt(32)
	s_waitcnt lgkmcnt(0)
	s_barrier
	s_setprio 1
	s_waitcnt lgkmcnt(0)
	v_mfma_f32_16x16x32_bf16 v[60:63], v[144:147], v[182:185], 0
	v_mfma_f32_16x16x32_bf16 v[56:59], v[158:161], v[182:185], 0
	v_mfma_f32_16x16x32_bf16 v[44:47], v[144:147], v[190:193], 0
	v_mfma_f32_16x16x32_bf16 v[40:43], v[158:161], v[190:193], 0
	v_mfma_f32_16x16x32_bf16 v[28:31], v[144:147], v[198:201], 0
	v_mfma_f32_16x16x32_bf16 v[24:27], v[158:161], v[198:201], 0
	v_mfma_f32_16x16x32_bf16 v[12:15], v[144:147], v[208:211], 0
	v_mfma_f32_16x16x32_bf16 v[8:11], v[158:161], v[208:211], 0
	v_mfma_f32_16x16x32_bf16 v[60:63], v[148:151], v[186:189], v[60:63]
	v_mfma_f32_16x16x32_bf16 v[56:59], v[162:165], v[186:189], v[56:59]
	v_mfma_f32_16x16x32_bf16 v[44:47], v[148:151], v[194:197], v[44:47]
	v_mfma_f32_16x16x32_bf16 v[40:43], v[162:165], v[194:197], v[40:43]
	v_mfma_f32_16x16x32_bf16 v[28:31], v[148:151], v[202:205], v[28:31]
	v_mfma_f32_16x16x32_bf16 v[24:27], v[162:165], v[202:205], v[24:27]
	v_mfma_f32_16x16x32_bf16 v[12:15], v[148:151], v[226:229], v[12:15]
	v_mfma_f32_16x16x32_bf16 v[8:11], v[162:165], v[226:229], v[8:11]
	s_setprio 0
	s_setprio 1
	v_mfma_f32_16x16x32_bf16 v[52:55], v[166:169], v[182:185], 0
	v_mfma_f32_16x16x32_bf16 v[48:51], v[174:177], v[182:185], 0
	v_mfma_f32_16x16x32_bf16 v[36:39], v[166:169], v[190:193], 0
	v_mfma_f32_16x16x32_bf16 v[32:35], v[174:177], v[190:193], 0
	v_mfma_f32_16x16x32_bf16 v[20:23], v[166:169], v[198:201], 0
	v_mfma_f32_16x16x32_bf16 v[16:19], v[174:177], v[198:201], 0
	v_mfma_f32_16x16x32_bf16 v[4:7], v[166:169], v[208:211], 0
	v_mfma_f32_16x16x32_bf16 v[0:3], v[174:177], v[208:211], 0
	v_mfma_f32_16x16x32_bf16 v[52:55], v[170:173], v[186:189], v[52:55]
	v_mfma_f32_16x16x32_bf16 v[48:51], v[178:181], v[186:189], v[48:51]
	v_mfma_f32_16x16x32_bf16 v[36:39], v[170:173], v[194:197], v[36:39]
	v_mfma_f32_16x16x32_bf16 v[32:35], v[178:181], v[194:197], v[32:35]
	v_mfma_f32_16x16x32_bf16 v[20:23], v[170:173], v[202:205], v[20:23]
	v_mfma_f32_16x16x32_bf16 v[16:19], v[178:181], v[202:205], v[16:19]
	v_mfma_f32_16x16x32_bf16 v[4:7], v[170:173], v[226:229], v[4:7]
	v_mfma_f32_16x16x32_bf16 v[0:3], v[178:181], v[226:229], v[0:3]
	s_setprio 0
	s_barrier
	s_add_i32 s1, 0, 0x18000
	v_add_u32_e32 v100, s1, v154
	s_add_i32 s33, 0, 0x1c000
	ds_read_b128 v[144:147], v100
	ds_read_b128 v[148:151], v100 offset:1024
	ds_read_b128 v[158:161], v100 offset:2048
	ds_read_b128 v[162:165], v100 offset:3072
	v_add_u32_e32 v100, s33, v154
	ds_read_b128 v[166:169], v100
	ds_read_b128 v[170:173], v100 offset:1024
	ds_read_b128 v[174:177], v100 offset:2048
	ds_read_b128 v[178:181], v100 offset:3072
	s_add_u32 s28, s28, 0x40000
	s_addc_u32 s29, s29, 0
	s_mov_b32 m0, s61
	v_lshl_add_u64 v[234:235], s[28:29], 0, v[130:131]
	ds_read_b128 v[182:185], v156 offset:32768
	ds_read_b128 v[186:189], v156 offset:33792
	ds_read_b128 v[190:193], v156 offset:34816
	ds_read_b128 v[194:197], v156 offset:35840
	ds_read_b128 v[198:201], v156 offset:36864
	ds_read_b128 v[202:205], v156 offset:37888
	ds_read_b128 v[208:211], v156 offset:38912
	ds_read_b128 v[226:229], v156 offset:39936
	global_load_lds_dwordx4 v[234:235], off
	v_lshl_add_u64 v[234:235], s[28:29], 0, v[134:135]
	s_mov_b32 m0, s69
	s_nop 0
	global_load_lds_dwordx4 v[234:235], off
	s_waitcnt vmcnt(32)
	s_waitcnt lgkmcnt(0)
	s_barrier
	s_setprio 1
	s_waitcnt lgkmcnt(0)
	v_mfma_f32_16x16x32_bf16 v[126:129], v[144:147], v[182:185], v[126:129]
	v_mfma_f32_16x16x32_bf16 v[122:125], v[158:161], v[182:185], v[122:125]
	v_mfma_f32_16x16x32_bf16 v[110:113], v[144:147], v[190:193], v[110:113]
	v_mfma_f32_16x16x32_bf16 v[106:109], v[158:161], v[190:193], v[106:109]
	v_mfma_f32_16x16x32_bf16 v[92:95], v[144:147], v[198:201], v[92:95]
	v_mfma_f32_16x16x32_bf16 v[88:91], v[158:161], v[198:201], v[88:91]
	v_mfma_f32_16x16x32_bf16 v[76:79], v[144:147], v[208:211], v[76:79]
	v_mfma_f32_16x16x32_bf16 v[72:75], v[158:161], v[208:211], v[72:75]
	v_mfma_f32_16x16x32_bf16 v[126:129], v[148:151], v[186:189], v[126:129]
	v_mfma_f32_16x16x32_bf16 v[122:125], v[162:165], v[186:189], v[122:125]
	v_mfma_f32_16x16x32_bf16 v[110:113], v[148:151], v[194:197], v[110:113]
	v_mfma_f32_16x16x32_bf16 v[106:109], v[162:165], v[194:197], v[106:109]
	v_mfma_f32_16x16x32_bf16 v[92:95], v[148:151], v[202:205], v[92:95]
	v_mfma_f32_16x16x32_bf16 v[88:91], v[162:165], v[202:205], v[88:91]
	v_mfma_f32_16x16x32_bf16 v[76:79], v[148:151], v[226:229], v[76:79]
	v_mfma_f32_16x16x32_bf16 v[72:75], v[162:165], v[226:229], v[72:75]
	s_setprio 0
	s_setprio 1
	v_mfma_f32_16x16x32_bf16 v[118:121], v[166:169], v[182:185], v[118:121]
	v_mfma_f32_16x16x32_bf16 v[114:117], v[174:177], v[182:185], v[114:117]
	v_mfma_f32_16x16x32_bf16 v[102:105], v[166:169], v[190:193], v[102:105]
	v_mfma_f32_16x16x32_bf16 v[96:99], v[174:177], v[190:193], v[96:99]
	v_mfma_f32_16x16x32_bf16 v[84:87], v[166:169], v[198:201], v[84:87]
	v_mfma_f32_16x16x32_bf16 v[80:83], v[174:177], v[198:201], v[80:83]
	v_mfma_f32_16x16x32_bf16 v[68:71], v[166:169], v[208:211], v[68:71]
	v_mfma_f32_16x16x32_bf16 v[64:67], v[174:177], v[208:211], v[64:67]
	v_mfma_f32_16x16x32_bf16 v[118:121], v[170:173], v[186:189], v[118:121]
	v_mfma_f32_16x16x32_bf16 v[114:117], v[178:181], v[186:189], v[114:117]
	v_mfma_f32_16x16x32_bf16 v[102:105], v[170:173], v[194:197], v[102:105]
	v_mfma_f32_16x16x32_bf16 v[96:99], v[178:181], v[194:197], v[96:99]
	v_mfma_f32_16x16x32_bf16 v[84:87], v[170:173], v[202:205], v[84:87]
	v_mfma_f32_16x16x32_bf16 v[80:83], v[178:181], v[202:205], v[80:83]
	v_mfma_f32_16x16x32_bf16 v[68:71], v[170:173], v[226:229], v[68:71]
	v_mfma_f32_16x16x32_bf16 v[64:67], v[178:181], v[226:229], v[64:67]
	s_setprio 0
	s_barrier
	s_add_i32 s1, s1, s34
	v_lshl_add_u64 v[152:153], v[152:153], 0, s[86:87]
	s_mov_b32 m0, s1
	ds_read_b128 v[182:185], v156 offset:49152
	ds_read_b128 v[186:189], v156 offset:50176
	ds_read_b128 v[190:193], v156 offset:51200
	ds_read_b128 v[194:197], v156 offset:52224
	ds_read_b128 v[198:201], v156 offset:53248
	ds_read_b128 v[202:205], v156 offset:54272
	ds_read_b128 v[208:211], v156 offset:55296
	ds_read_b128 v[226:229], v156 offset:56320
	global_load_lds_dwordx4 v[152:153], off
	s_add_i32 m0, s1, 0x2000
	s_add_u32 s14, s14, 0x40080
	v_lshl_add_u64 v[152:153], v[212:213], 0, s[86:87]
	s_addc_u32 s15, s15, 0
	s_add_i32 s1, s33, s34
	global_load_lds_dwordx4 v[152:153], off
	v_lshl_add_u64 v[152:153], s[14:15], 0, v[132:133]
	s_mov_b32 m0, s1
	s_nop 0
	global_load_lds_dwordx4 v[152:153], off
	v_lshl_add_u64 v[152:153], s[14:15], 0, v[136:137]
	s_add_i32 m0, s1, 0x2000
	s_nop 0
	global_load_lds_dwordx4 v[152:153], off
	v_lshl_add_u64 v[152:153], v[230:231], 0, s[86:87]
	s_mov_b32 m0, s89
	s_nop 0
	global_load_lds_dwordx4 v[152:153], off
	v_lshl_add_u64 v[152:153], v[232:233], 0, s[86:87]
	s_mov_b32 m0, s92
	s_nop 0
	global_load_lds_dwordx4 v[152:153], off
	s_waitcnt vmcnt(24)
	s_waitcnt lgkmcnt(0)
	s_barrier
	s_setprio 1
	s_waitcnt lgkmcnt(0)
	v_mfma_f32_16x16x32_bf16 v[60:63], v[144:147], v[182:185], v[60:63]
	v_mfma_f32_16x16x32_bf16 v[56:59], v[158:161], v[182:185], v[56:59]
	v_mfma_f32_16x16x32_bf16 v[44:47], v[144:147], v[190:193], v[44:47]
	v_mfma_f32_16x16x32_bf16 v[40:43], v[158:161], v[190:193], v[40:43]
	v_mfma_f32_16x16x32_bf16 v[28:31], v[144:147], v[198:201], v[28:31]
	v_mfma_f32_16x16x32_bf16 v[24:27], v[158:161], v[198:201], v[24:27]
	v_mfma_f32_16x16x32_bf16 v[12:15], v[144:147], v[208:211], v[12:15]
	v_mfma_f32_16x16x32_bf16 v[8:11], v[158:161], v[208:211], v[8:11]
	v_mfma_f32_16x16x32_bf16 v[60:63], v[148:151], v[186:189], v[60:63]
	v_mfma_f32_16x16x32_bf16 v[56:59], v[162:165], v[186:189], v[56:59]
	v_mfma_f32_16x16x32_bf16 v[44:47], v[148:151], v[194:197], v[44:47]
	v_mfma_f32_16x16x32_bf16 v[40:43], v[162:165], v[194:197], v[40:43]
	v_mfma_f32_16x16x32_bf16 v[28:31], v[148:151], v[202:205], v[28:31]
	v_mfma_f32_16x16x32_bf16 v[24:27], v[162:165], v[202:205], v[24:27]
	v_mfma_f32_16x16x32_bf16 v[12:15], v[148:151], v[226:229], v[12:15]
	v_mfma_f32_16x16x32_bf16 v[8:11], v[162:165], v[226:229], v[8:11]
	s_setprio 0
	s_setprio 1
	v_mfma_f32_16x16x32_bf16 v[52:55], v[166:169], v[182:185], v[52:55]
	v_mfma_f32_16x16x32_bf16 v[48:51], v[174:177], v[182:185], v[48:51]
	v_mfma_f32_16x16x32_bf16 v[36:39], v[166:169], v[190:193], v[36:39]
	v_mfma_f32_16x16x32_bf16 v[32:35], v[174:177], v[190:193], v[32:35]
	v_mfma_f32_16x16x32_bf16 v[20:23], v[166:169], v[198:201], v[20:23]
	v_mfma_f32_16x16x32_bf16 v[16:19], v[174:177], v[198:201], v[16:19]
	v_mfma_f32_16x16x32_bf16 v[4:7], v[166:169], v[208:211], v[4:7]
	v_mfma_f32_16x16x32_bf16 v[0:3], v[174:177], v[208:211], v[0:3]
	v_mfma_f32_16x16x32_bf16 v[52:55], v[170:173], v[186:189], v[52:55]
	v_mfma_f32_16x16x32_bf16 v[48:51], v[178:181], v[186:189], v[48:51]
	v_mfma_f32_16x16x32_bf16 v[36:39], v[170:173], v[194:197], v[36:39]
	v_mfma_f32_16x16x32_bf16 v[32:35], v[178:181], v[194:197], v[32:35]
	v_mfma_f32_16x16x32_bf16 v[20:23], v[170:173], v[202:205], v[20:23]
	v_mfma_f32_16x16x32_bf16 v[16:19], v[178:181], v[202:205], v[16:19]
	v_mfma_f32_16x16x32_bf16 v[4:7], v[170:173], v[226:229], v[4:7]
	v_mfma_f32_16x16x32_bf16 v[0:3], v[178:181], v[226:229], v[0:3]
	s_setprio 0
	s_barrier
	s_add_i32 s73, s73, 2
	s_add_u32 s12, s12, 0x100
	s_addc_u32 s13, s13, 0
	s_add_u32 s54, s54, 0x100
	s_addc_u32 s55, s55, 0
.LBB0_396:
	s_add_u32 s1, s12, 0xfffc0080
	s_addc_u32 s14, s13, -1
	s_add_i32 s33, 0, 0x10000
	s_cmp_eq_u32 s73, 12
	s_cselect_b32 s29, s11, s14
	s_cselect_b32 s28, s30, s1
	v_add_u32_e32 v100, s33, v154
	s_cselect_b32 s15, s31, s55
	s_cselect_b32 s14, s47, s54
	s_add_i32 s1, 0, 0x14000
	ds_read_b128 v[144:147], v100
	ds_read_b128 v[148:151], v100 offset:1024
	ds_read_b128 v[158:161], v100 offset:2048
	ds_read_b128 v[162:165], v100 offset:3072
	v_add_u32_e32 v100, s1, v154
	ds_read_b128 v[166:169], v100
	ds_read_b128 v[170:173], v100 offset:1024
	ds_read_b128 v[174:177], v100 offset:2048
	ds_read_b128 v[178:181], v100 offset:3072
	v_lshl_add_u64 v[152:153], s[12:13], 0, v[140:141]
	s_add_i32 m0, s41, 0xc000
	ds_read_b128 v[182:185], v156
	ds_read_b128 v[186:189], v156 offset:1024
	ds_read_b128 v[190:193], v156 offset:2048
	ds_read_b128 v[194:197], v156 offset:3072
	ds_read_b128 v[198:201], v156 offset:4096
	ds_read_b128 v[202:205], v156 offset:5120
	ds_read_b128 v[208:211], v156 offset:6144
	ds_read_b128 v[226:229], v156 offset:7168
	global_load_lds_dwordx4 v[152:153], off
	v_lshl_add_u64 v[152:153], s[12:13], 0, v[142:143]
	s_add_i32 m0, s41, 0xe000
	s_nop 0
	global_load_lds_dwordx4 v[152:153], off
	s_waitcnt vmcnt(8)
	s_waitcnt lgkmcnt(0)
	s_barrier
	s_setprio 1
	s_waitcnt lgkmcnt(0)
	v_mfma_f32_16x16x32_bf16 v[126:129], v[144:147], v[182:185], v[126:129]
	v_mfma_f32_16x16x32_bf16 v[122:125], v[158:161], v[182:185], v[122:125]
	v_mfma_f32_16x16x32_bf16 v[110:113], v[144:147], v[190:193], v[110:113]
	v_mfma_f32_16x16x32_bf16 v[106:109], v[158:161], v[190:193], v[106:109]
	v_mfma_f32_16x16x32_bf16 v[92:95], v[144:147], v[198:201], v[92:95]
	v_mfma_f32_16x16x32_bf16 v[88:91], v[158:161], v[198:201], v[88:91]
	v_mfma_f32_16x16x32_bf16 v[76:79], v[144:147], v[208:211], v[76:79]
	v_mfma_f32_16x16x32_bf16 v[72:75], v[158:161], v[208:211], v[72:75]
	v_mfma_f32_16x16x32_bf16 v[126:129], v[148:151], v[186:189], v[126:129]
	v_mfma_f32_16x16x32_bf16 v[122:125], v[162:165], v[186:189], v[122:125]
	v_mfma_f32_16x16x32_bf16 v[110:113], v[148:151], v[194:197], v[110:113]
	v_mfma_f32_16x16x32_bf16 v[106:109], v[162:165], v[194:197], v[106:109]
	v_mfma_f32_16x16x32_bf16 v[92:95], v[148:151], v[202:205], v[92:95]
	v_mfma_f32_16x16x32_bf16 v[88:91], v[162:165], v[202:205], v[88:91]
	v_mfma_f32_16x16x32_bf16 v[76:79], v[148:151], v[226:229], v[76:79]
	v_mfma_f32_16x16x32_bf16 v[72:75], v[162:165], v[226:229], v[72:75]
	s_setprio 0
	s_setprio 1
	v_mfma_f32_16x16x32_bf16 v[118:121], v[166:169], v[182:185], v[118:121]
	v_mfma_f32_16x16x32_bf16 v[114:117], v[174:177], v[182:185], v[114:117]
	v_mfma_f32_16x16x32_bf16 v[102:105], v[166:169], v[190:193], v[102:105]
	v_mfma_f32_16x16x32_bf16 v[96:99], v[174:177], v[190:193], v[96:99]
	v_mfma_f32_16x16x32_bf16 v[84:87], v[166:169], v[198:201], v[84:87]
	v_mfma_f32_16x16x32_bf16 v[80:83], v[174:177], v[198:201], v[80:83]
	v_mfma_f32_16x16x32_bf16 v[68:71], v[166:169], v[208:211], v[68:71]
	v_mfma_f32_16x16x32_bf16 v[64:67], v[174:177], v[208:211], v[64:67]
	v_mfma_f32_16x16x32_bf16 v[118:121], v[170:173], v[186:189], v[118:121]
	v_mfma_f32_16x16x32_bf16 v[114:117], v[178:181], v[186:189], v[114:117]
	v_mfma_f32_16x16x32_bf16 v[102:105], v[170:173], v[194:197], v[102:105]
	v_mfma_f32_16x16x32_bf16 v[96:99], v[178:181], v[194:197], v[96:99]
	v_mfma_f32_16x16x32_bf16 v[84:87], v[170:173], v[202:205], v[84:87]
	v_mfma_f32_16x16x32_bf16 v[80:83], v[178:181], v[202:205], v[80:83]
	v_mfma_f32_16x16x32_bf16 v[68:71], v[170:173], v[226:229], v[68:71]
	v_mfma_f32_16x16x32_bf16 v[64:67], v[178:181], v[226:229], v[64:67]
	s_setprio 0
	s_barrier
	s_add_i32 s33, s33, s34
	v_lshl_add_u64 v[152:153], s[14:15], 0, v[132:133]
	s_mov_b32 m0, s33
	ds_read_b128 v[182:185], v156 offset:16384
	ds_read_b128 v[186:189], v156 offset:17408
	ds_read_b128 v[190:193], v156 offset:18432
	ds_read_b128 v[194:197], v156 offset:19456
	ds_read_b128 v[198:201], v156 offset:20480
	ds_read_b128 v[202:205], v156 offset:21504
	ds_read_b128 v[208:211], v156 offset:22528
	ds_read_b128 v[226:229], v156 offset:23552
	global_load_lds_dwordx4 v[152:153], off
	s_add_i32 m0, s33, 0x2000
	s_add_u32 s80, s14, 0x40000
	v_lshl_add_u64 v[212:213], s[14:15], 0, v[136:137]
	s_addc_u32 s81, s15, 0
	s_add_i32 s1, s1, s34
	global_load_lds_dwordx4 v[212:213], off
	v_lshl_add_u64 v[230:231], s[80:81], 0, v[132:133]
	s_mov_b32 m0, s1
	v_lshl_add_u64 v[232:233], s[28:29], 0, v[134:135]
	global_load_lds_dwordx4 v[230:231], off
	v_lshl_add_u64 v[230:231], s[80:81], 0, v[136:137]
	s_add_i32 m0, s1, 0x2000
	s_nop 0
	global_load_lds_dwordx4 v[230:231], off
	v_lshl_add_u64 v[230:231], s[28:29], 0, v[130:131]
	s_mov_b32 m0, s41
	s_nop 0
	global_load_lds_dwordx4 v[230:231], off
	s_mov_b32 m0, s60
	s_nop 0
	global_load_lds_dwordx4 v[232:233], off
	s_waitcnt vmcnt(8)
	s_waitcnt lgkmcnt(0)
	s_barrier
	s_setprio 1
	s_waitcnt lgkmcnt(0)
	v_mfma_f32_16x16x32_bf16 v[60:63], v[144:147], v[182:185], v[60:63]
	v_mfma_f32_16x16x32_bf16 v[56:59], v[158:161], v[182:185], v[56:59]
	v_mfma_f32_16x16x32_bf16 v[44:47], v[144:147], v[190:193], v[44:47]
	v_mfma_f32_16x16x32_bf16 v[40:43], v[158:161], v[190:193], v[40:43]
	v_mfma_f32_16x16x32_bf16 v[28:31], v[144:147], v[198:201], v[28:31]
	v_mfma_f32_16x16x32_bf16 v[24:27], v[158:161], v[198:201], v[24:27]
	v_mfma_f32_16x16x32_bf16 v[12:15], v[144:147], v[208:211], v[12:15]
	v_mfma_f32_16x16x32_bf16 v[8:11], v[158:161], v[208:211], v[8:11]
	v_mfma_f32_16x16x32_bf16 v[60:63], v[148:151], v[186:189], v[60:63]
	v_mfma_f32_16x16x32_bf16 v[56:59], v[162:165], v[186:189], v[56:59]
	v_mfma_f32_16x16x32_bf16 v[44:47], v[148:151], v[194:197], v[44:47]
	v_mfma_f32_16x16x32_bf16 v[40:43], v[162:165], v[194:197], v[40:43]
	v_mfma_f32_16x16x32_bf16 v[28:31], v[148:151], v[202:205], v[28:31]
	v_mfma_f32_16x16x32_bf16 v[24:27], v[162:165], v[202:205], v[24:27]
	v_mfma_f32_16x16x32_bf16 v[12:15], v[148:151], v[226:229], v[12:15]
	v_mfma_f32_16x16x32_bf16 v[8:11], v[162:165], v[226:229], v[8:11]
	s_setprio 0
	s_setprio 1
	v_mfma_f32_16x16x32_bf16 v[52:55], v[166:169], v[182:185], v[52:55]
	v_mfma_f32_16x16x32_bf16 v[48:51], v[174:177], v[182:185], v[48:51]
	v_mfma_f32_16x16x32_bf16 v[36:39], v[166:169], v[190:193], v[36:39]
	v_mfma_f32_16x16x32_bf16 v[32:35], v[174:177], v[190:193], v[32:35]
	v_mfma_f32_16x16x32_bf16 v[20:23], v[166:169], v[198:201], v[20:23]
	v_mfma_f32_16x16x32_bf16 v[16:19], v[174:177], v[198:201], v[16:19]
	v_mfma_f32_16x16x32_bf16 v[4:7], v[166:169], v[208:211], v[4:7]
	v_mfma_f32_16x16x32_bf16 v[0:3], v[174:177], v[208:211], v[0:3]
	v_mfma_f32_16x16x32_bf16 v[52:55], v[170:173], v[186:189], v[52:55]
	v_mfma_f32_16x16x32_bf16 v[48:51], v[178:181], v[186:189], v[48:51]
	v_mfma_f32_16x16x32_bf16 v[36:39], v[170:173], v[194:197], v[36:39]
	v_mfma_f32_16x16x32_bf16 v[32:35], v[178:181], v[194:197], v[32:35]
	v_mfma_f32_16x16x32_bf16 v[20:23], v[170:173], v[202:205], v[20:23]
	v_mfma_f32_16x16x32_bf16 v[16:19], v[178:181], v[202:205], v[16:19]
	v_mfma_f32_16x16x32_bf16 v[4:7], v[170:173], v[226:229], v[4:7]
	v_mfma_f32_16x16x32_bf16 v[0:3], v[178:181], v[226:229], v[0:3]
	s_setprio 0
	s_barrier
	s_add_i32 s1, 0, 0x18000
	v_add_u32_e32 v100, s1, v154
	s_add_i32 s33, 0, 0x1c000
	ds_read_b128 v[144:147], v100
	ds_read_b128 v[148:151], v100 offset:1024
	ds_read_b128 v[158:161], v100 offset:2048
	ds_read_b128 v[162:165], v100 offset:3072
	v_add_u32_e32 v100, s33, v154
	ds_read_b128 v[166:169], v100
	ds_read_b128 v[170:173], v100 offset:1024
	ds_read_b128 v[174:177], v100 offset:2048
	ds_read_b128 v[178:181], v100 offset:3072
	s_add_u32 s28, s28, 0x40000
	s_addc_u32 s29, s29, 0
	s_mov_b32 m0, s61
	v_lshl_add_u64 v[234:235], s[28:29], 0, v[130:131]
	ds_read_b128 v[182:185], v156 offset:32768
	ds_read_b128 v[186:189], v156 offset:33792
	ds_read_b128 v[190:193], v156 offset:34816
	ds_read_b128 v[194:197], v156 offset:35840
	ds_read_b128 v[198:201], v156 offset:36864
	ds_read_b128 v[202:205], v156 offset:37888
	ds_read_b128 v[208:211], v156 offset:38912
	ds_read_b128 v[226:229], v156 offset:39936
	global_load_lds_dwordx4 v[234:235], off
	v_lshl_add_u64 v[234:235], s[28:29], 0, v[134:135]
	s_mov_b32 m0, s69
	s_nop 0
	global_load_lds_dwordx4 v[234:235], off
	s_waitcnt vmcnt(8)
	s_waitcnt lgkmcnt(0)
	s_barrier
	s_setprio 1
	s_waitcnt lgkmcnt(0)
	v_mfma_f32_16x16x32_bf16 v[126:129], v[144:147], v[182:185], v[126:129]
	v_mfma_f32_16x16x32_bf16 v[122:125], v[158:161], v[182:185], v[122:125]
	v_mfma_f32_16x16x32_bf16 v[110:113], v[144:147], v[190:193], v[110:113]
	v_mfma_f32_16x16x32_bf16 v[106:109], v[158:161], v[190:193], v[106:109]
	v_mfma_f32_16x16x32_bf16 v[92:95], v[144:147], v[198:201], v[92:95]
	v_mfma_f32_16x16x32_bf16 v[88:91], v[158:161], v[198:201], v[88:91]
	v_mfma_f32_16x16x32_bf16 v[76:79], v[144:147], v[208:211], v[76:79]
	v_mfma_f32_16x16x32_bf16 v[72:75], v[158:161], v[208:211], v[72:75]
	v_mfma_f32_16x16x32_bf16 v[126:129], v[148:151], v[186:189], v[126:129]
	v_mfma_f32_16x16x32_bf16 v[122:125], v[162:165], v[186:189], v[122:125]
	v_mfma_f32_16x16x32_bf16 v[110:113], v[148:151], v[194:197], v[110:113]
	v_mfma_f32_16x16x32_bf16 v[106:109], v[162:165], v[194:197], v[106:109]
	v_mfma_f32_16x16x32_bf16 v[92:95], v[148:151], v[202:205], v[92:95]
	v_mfma_f32_16x16x32_bf16 v[88:91], v[162:165], v[202:205], v[88:91]
	v_mfma_f32_16x16x32_bf16 v[76:79], v[148:151], v[226:229], v[76:79]
	v_mfma_f32_16x16x32_bf16 v[72:75], v[162:165], v[226:229], v[72:75]
	s_setprio 0
	s_setprio 1
	v_mfma_f32_16x16x32_bf16 v[118:121], v[166:169], v[182:185], v[118:121]
	v_mfma_f32_16x16x32_bf16 v[114:117], v[174:177], v[182:185], v[114:117]
	v_mfma_f32_16x16x32_bf16 v[102:105], v[166:169], v[190:193], v[102:105]
	v_mfma_f32_16x16x32_bf16 v[96:99], v[174:177], v[190:193], v[96:99]
	v_mfma_f32_16x16x32_bf16 v[84:87], v[166:169], v[198:201], v[84:87]
	v_mfma_f32_16x16x32_bf16 v[80:83], v[174:177], v[198:201], v[80:83]
	v_mfma_f32_16x16x32_bf16 v[68:71], v[166:169], v[208:211], v[68:71]
	v_mfma_f32_16x16x32_bf16 v[64:67], v[174:177], v[208:211], v[64:67]
	v_mfma_f32_16x16x32_bf16 v[118:121], v[170:173], v[186:189], v[118:121]
	v_mfma_f32_16x16x32_bf16 v[114:117], v[178:181], v[186:189], v[114:117]
	v_mfma_f32_16x16x32_bf16 v[102:105], v[170:173], v[194:197], v[102:105]
	v_mfma_f32_16x16x32_bf16 v[96:99], v[178:181], v[194:197], v[96:99]
	v_mfma_f32_16x16x32_bf16 v[84:87], v[170:173], v[202:205], v[84:87]
	v_mfma_f32_16x16x32_bf16 v[80:83], v[178:181], v[202:205], v[80:83]
	v_mfma_f32_16x16x32_bf16 v[68:71], v[170:173], v[226:229], v[68:71]
	v_mfma_f32_16x16x32_bf16 v[64:67], v[178:181], v[226:229], v[64:67]
	s_setprio 0
	s_barrier
	s_add_i32 s1, s1, s34
	v_lshl_add_u64 v[152:153], v[152:153], 0, s[86:87]
	s_mov_b32 m0, s1
	ds_read_b128 v[182:185], v156 offset:49152
	ds_read_b128 v[186:189], v156 offset:50176
	ds_read_b128 v[190:193], v156 offset:51200
	ds_read_b128 v[194:197], v156 offset:52224
	ds_read_b128 v[198:201], v156 offset:53248
	ds_read_b128 v[202:205], v156 offset:54272
	ds_read_b128 v[208:211], v156 offset:55296
	ds_read_b128 v[226:229], v156 offset:56320
	global_load_lds_dwordx4 v[152:153], off
	s_add_i32 m0, s1, 0x2000
	s_add_u32 s14, s14, 0x40080
	v_lshl_add_u64 v[152:153], v[212:213], 0, s[86:87]
	s_addc_u32 s15, s15, 0
	s_add_i32 s1, s33, s34
	global_load_lds_dwordx4 v[152:153], off
	v_lshl_add_u64 v[152:153], s[14:15], 0, v[132:133]
	s_mov_b32 m0, s1
	s_nop 0
	global_load_lds_dwordx4 v[152:153], off
	v_lshl_add_u64 v[152:153], s[14:15], 0, v[136:137]
	s_add_i32 m0, s1, 0x2000
	s_nop 0
	global_load_lds_dwordx4 v[152:153], off
	v_lshl_add_u64 v[152:153], v[230:231], 0, s[86:87]
	s_mov_b32 m0, s89
	s_nop 0
	global_load_lds_dwordx4 v[152:153], off
	v_lshl_add_u64 v[152:153], v[232:233], 0, s[86:87]
	s_mov_b32 m0, s92
	s_nop 0
	global_load_lds_dwordx4 v[152:153], off
	s_waitcnt vmcnt(8)
	s_waitcnt lgkmcnt(0)
	s_barrier
	s_setprio 1
	s_waitcnt lgkmcnt(0)
	v_mfma_f32_16x16x32_bf16 v[60:63], v[144:147], v[182:185], v[60:63]
	v_mfma_f32_16x16x32_bf16 v[56:59], v[158:161], v[182:185], v[56:59]
	v_mfma_f32_16x16x32_bf16 v[44:47], v[144:147], v[190:193], v[44:47]
	v_mfma_f32_16x16x32_bf16 v[40:43], v[158:161], v[190:193], v[40:43]
	v_mfma_f32_16x16x32_bf16 v[28:31], v[144:147], v[198:201], v[28:31]
	v_mfma_f32_16x16x32_bf16 v[24:27], v[158:161], v[198:201], v[24:27]
	v_mfma_f32_16x16x32_bf16 v[12:15], v[144:147], v[208:211], v[12:15]
	v_mfma_f32_16x16x32_bf16 v[8:11], v[158:161], v[208:211], v[8:11]
	v_mfma_f32_16x16x32_bf16 v[60:63], v[148:151], v[186:189], v[60:63]
	v_mfma_f32_16x16x32_bf16 v[56:59], v[162:165], v[186:189], v[56:59]
	v_mfma_f32_16x16x32_bf16 v[44:47], v[148:151], v[194:197], v[44:47]
	v_mfma_f32_16x16x32_bf16 v[40:43], v[162:165], v[194:197], v[40:43]
	v_mfma_f32_16x16x32_bf16 v[28:31], v[148:151], v[202:205], v[28:31]
	v_mfma_f32_16x16x32_bf16 v[24:27], v[162:165], v[202:205], v[24:27]
	v_mfma_f32_16x16x32_bf16 v[12:15], v[148:151], v[226:229], v[12:15]
	v_mfma_f32_16x16x32_bf16 v[8:11], v[162:165], v[226:229], v[8:11]
	s_setprio 0
	s_setprio 1
	v_mfma_f32_16x16x32_bf16 v[52:55], v[166:169], v[182:185], v[52:55]
	v_mfma_f32_16x16x32_bf16 v[48:51], v[174:177], v[182:185], v[48:51]
	v_mfma_f32_16x16x32_bf16 v[36:39], v[166:169], v[190:193], v[36:39]
	v_mfma_f32_16x16x32_bf16 v[32:35], v[174:177], v[190:193], v[32:35]
	v_mfma_f32_16x16x32_bf16 v[20:23], v[166:169], v[198:201], v[20:23]
	v_mfma_f32_16x16x32_bf16 v[16:19], v[174:177], v[198:201], v[16:19]
	v_mfma_f32_16x16x32_bf16 v[4:7], v[166:169], v[208:211], v[4:7]
	v_mfma_f32_16x16x32_bf16 v[0:3], v[174:177], v[208:211], v[0:3]
	v_mfma_f32_16x16x32_bf16 v[52:55], v[170:173], v[186:189], v[52:55]
	v_mfma_f32_16x16x32_bf16 v[48:51], v[178:181], v[186:189], v[48:51]
	v_mfma_f32_16x16x32_bf16 v[36:39], v[170:173], v[194:197], v[36:39]
	v_mfma_f32_16x16x32_bf16 v[32:35], v[178:181], v[194:197], v[32:35]
	v_mfma_f32_16x16x32_bf16 v[20:23], v[170:173], v[202:205], v[20:23]
	v_mfma_f32_16x16x32_bf16 v[16:19], v[178:181], v[202:205], v[16:19]
	v_mfma_f32_16x16x32_bf16 v[4:7], v[170:173], v[226:229], v[4:7]
	v_mfma_f32_16x16x32_bf16 v[0:3], v[178:181], v[226:229], v[0:3]
	s_setprio 0
	s_barrier
	s_add_i32 s73, s73, 2
	s_add_u32 s12, s12, 0x100
	s_addc_u32 s13, s13, 0
	s_add_u32 s54, s54, 0x100
	s_addc_u32 s55, s55, 0
	s_cmp_gt_u32 s73, 13
	s_cbranch_scc0 .LBB0_396

.LBB0_401:
	s_cmp_lt_i32 s47, 2
	s_cselect_b64 s[30:31], -1, 0
	s_and_b64 s[30:31], s[30:31], s[64:65]
	s_orn2_b64 s[12:13], s[30:31], s[8:9]
	s_and_b64 vcc, exec, s[12:13]
	s_cbranch_vccnz .Lmy_b16_inplace
	s_cmp_lt_i32 s54, s49
	s_cselect_b32 s100, s25, 1.0
	s_lshl_b32 s1, s40, 8
	s_add_i32 s1, s1, s84
	s_and_b64 vcc, exec, s[58:59]
	s_cbranch_vccz .Lmy_b16_plain_d
	s_lshr_b32 s75, s33, 11
	s_lshl_b32 s55, s75, 1
	s_sub_i32 s73, 13, s55
	s_lshr_b32 s10, s1, 13
	s_mul_i32 s10, s10, 3
	s_add_i32 s10, s10, s75
	s_mov_b32 s11, 0
	s_lshl_b64 s[10:11], s[10:11], 25
	s_add_u32 s10, s22, s10
	s_addc_u32 s11, s23, s11
	s_lshl_b32 s12, s33, 14
	s_and_b32 s12, s12, 0x1e00000
	s_add_u32 s10, s10, s12
	s_addc_u32 s11, s11, 0
	s_lshl_b32 s12, s85, 1
	s_add_u32 s10, s10, s12
	s_addc_u32 s11, s11, 0
	s_and_b32 s12, s1, 0x1fff
	s_lshr_b32 s12, s12, s55
	s_lshl_b32 s12, s12, 8
	s_add_u32 s10, s10, s12
	s_addc_u32 s11, s11, 0
	s_lshr_b32 s12, 0x1000, s55
	s_lshr_b32 s13, 0x8000, s55
	s_mov_b32 s14, 0x200000
	s_lshl_b32 s15, 1, s55
	s_add_i32 s15, s15, -1
	v_lshrrev_b32_e32 v176, 2, v224
	v_and_b32_e32 v144, s15, v176
	v_lshlrev_b32_e32 v144, s73, v144
	v_lshrrev_b32_e32 v145, s55, v176
	v_add_lshl_u32 v144, v144, v145, 8
	v_and_b32_e32 v145, 3, v224
	v_lshl_add_u32 v144, v145, 4, v144
	s_branch .Lmy_b16_addr_d
.Lmy_b16_plain_d:
	s_cmp_lt_i32 s1, s57
	s_cselect_b64 s[12:13], -1, 0
	s_or_b64 s[12:13], s[12:13], s[16:17]
	s_cmp_lg_u64 s[12:13], 0
	s_cselect_b32 s10, s28, s18
	s_cselect_b32 s11, s29, s19
	s_cselect_b32 s12, 0, s57
	s_sub_i32 s12, s1, s12
	s_mul_hi_u32 s15, s12, s24
	s_mul_i32 s14, s12, s24
	s_add_i32 s12, s33, s85
	s_add_u32 s14, s14, s12
	s_addc_u32 s15, s15, 0
	s_lshl_b64 s[14:15], s[14:15], 1
	s_add_u32 s10, s10, s14
	s_addc_u32 s11, s11, s15
	s_lshl_b32 s12, s24, 5
	s_lshl_b32 s13, s24, 8
	s_movk_i32 s14, 0x100
	v_lshrrev_b32_e32 v176, 2, v224
	v_mul_lo_u32 v144, v176, s24
	v_and_b32_e32 v145, 3, v224
	v_lshlrev_b32_e32 v145, 3, v145
	v_add_lshl_u32 v144, v144, v145, 1
.Lmy_b16_addr_d:
	s_mov_b64 s[2:3], s[10:11]
	s_add_u32 s90, s10, s13
	s_addc_u32 s91, s11, 0
	s_mov_b32 s0, s12
	s_mov_b32 s32, s14
	s_mov_b32 s36, s100
	v_mov_b32_e32 v247, v144
	s_mov_b32 s37, 1
	s_branch .LBB0_391
.Lmy_b16_inplace:
	s_mov_b32 s37, 0
	s_and_b64 vcc, exec, s[70:71]
	s_cbranch_vccz .Lmy_b16_inplace2
	s_barrier
.Lmy_b16_inplace2:
	s_waitcnt vmcnt(8)
	s_cmp_lt_i32 s54, s49
	s_cselect_b32 s100, s25, 1.0
	s_lshl_b32 s1, s40, 8
	s_add_i32 s1, s1, s84
	s_and_b64 vcc, exec, s[58:59]
	s_cbranch_vccz .Lmy_b16_plain_i
	s_lshr_b32 s75, s33, 11
	s_lshl_b32 s55, s75, 1
	s_sub_i32 s73, 13, s55
	s_lshr_b32 s10, s1, 13
	s_mul_i32 s10, s10, 3
	s_add_i32 s10, s10, s75
	s_mov_b32 s11, 0
	s_lshl_b64 s[10:11], s[10:11], 25
	s_add_u32 s10, s22, s10
	s_addc_u32 s11, s23, s11
	s_lshl_b32 s12, s33, 14
	s_and_b32 s12, s12, 0x1e00000
	s_add_u32 s10, s10, s12
	s_addc_u32 s11, s11, 0
	s_lshl_b32 s12, s85, 1
	s_add_u32 s10, s10, s12
	s_addc_u32 s11, s11, 0
	s_and_b32 s12, s1, 0x1fff
	s_lshr_b32 s12, s12, s55
	s_lshl_b32 s12, s12, 8
	s_add_u32 s10, s10, s12
	s_addc_u32 s11, s11, 0
	s_lshr_b32 s12, 0x1000, s55
	s_lshr_b32 s13, 0x8000, s55
	s_mov_b32 s14, 0x200000
	s_lshl_b32 s15, 1, s55
	s_add_i32 s15, s15, -1
	v_lshrrev_b32_e32 v176, 2, v224
	v_and_b32_e32 v144, s15, v176
	v_lshlrev_b32_e32 v144, s73, v144
	v_lshrrev_b32_e32 v145, s55, v176
	v_add_lshl_u32 v144, v144, v145, 8
	v_and_b32_e32 v145, 3, v224
	v_lshl_add_u32 v144, v145, 4, v144
	s_branch .Lmy_b16_addr_i

.LBB0_480:
	v_readlane_b32 s0, v157, 0
	v_readlane_b32 s2, v157, 1
	v_readlane_b32 s3, v157, 2
	v_readlane_b32 s32, v157, 3
	v_readlane_b32 s36, v157, 4
	v_readlane_b32 s37, v157, 5
	v_readlane_b32 s46, v157, 6
	v_readlane_b32 s53, v157, 7
	v_readlane_b32 s56, v157, 8
	v_readlane_b32 s82, v157, 9
	v_readlane_b32 s90, v157, 10
	v_readlane_b32 s91, v157, 11
	v_readlane_b32 s97, v157, 12
	s_waitcnt vmcnt(0)
	s_barrier
